# v9 + residual-GEMM epilogues (G3, FFN-out L0, W_O): sum-of-squares shuffles via v_permlane16/32_swap instead of ds_bpermute
# speedup vs baseline: 1.0030x; 1.0030x over previous
.LBB0_523:
	v_mul_f32_e32 v129, v129, v129
	v_mul_f32_e32 v127, v127, v127
	v_mul_f32_e32 v176, v209, v209
	v_mul_f32_e32 v131, v131, v131
	v_fmac_f32_e32 v129, v128, v128
	v_fmac_f32_e32 v127, v126, v126
	v_fmac_f32_e32 v176, v208, v208
	v_fmac_f32_e32 v131, v130, v130
	v_add_f32_e32 v126, v129, v127
	v_mul_f32_e32 v127, v117, v117
	v_mul_f32_e32 v129, v119, v119
	v_add_f32_e32 v130, v176, v131
	v_fmac_f32_e32 v127, v116, v116
	v_fmac_f32_e32 v129, v118, v118
	v_add_f32_e32 v126, v130, v126
	v_add_f32_e32 v127, v127, v129
	v_mul_f32_e32 v129, v113, v113
	v_mul_f32_e32 v130, v115, v115
	v_fmac_f32_e32 v129, v112, v112
	v_fmac_f32_e32 v130, v114, v114
	v_add_f32_e32 v129, v129, v130
	v_add_f32_e32 v127, v127, v129
	v_and_b32_e32 v129, 64, v218
	v_add_f32_e32 v127, v126, v127
	v_xor_b32_e32 v126, 16, v218
	v_add_u32_e32 v129, 64, v129
	v_cmp_lt_i32_e32 vcc, v126, v129
	v_cvt_pk_bf16_f32 v116, v116, v117
	v_cvt_pk_bf16_f32 v117, v118, v119
	v_cvt_pk_bf16_f32 v118, v112, v113
	v_xor_b32_e32 v113, 32, v218
	v_add_u32_e32 v128, 0x80, v210
	v_cndmask_b32_e32 v126, v218, v126, vcc
	v_lshlrev_b32_e32 v126, 2, v126
	v_cmp_lt_i32_e32 vcc, v113, v129
	s_lshl_b32 s21, s30, 2
	v_mov_b32_e32 v129, v195
	v_cndmask_b32_e32 v113, v218, v113, vcc
	s_waitcnt lgkmcnt(0)
	v_mov_b32_e32 v130, v127
	v_mov_b32_e32 v253, v127
	s_nop 1
	v_permlane16_swap_b32_e32 v130, v253
	v_add_f32_e32 v112, v130, v253
	v_lshlrev_b32_e32 v127, 2, v113
	v_cmp_eq_u32_e64 s[8:9], 0, v220
	s_or_b32 s21, s21, s42
	v_cvt_pk_bf16_f32 v119, v114, v115
	v_lshl_add_u64 v[114:115], v[128:129], 1, s[72:73]
	global_store_dwordx4 v[114:115], v[116:119], off
	v_mov_b32_e32 v113, v112
	v_mov_b32_e32 v253, v112
	s_nop 1
	v_permlane32_swap_b32_e32 v113, v253
	v_add_f32_e32 v114, v113, v253
	s_and_saveexec_b64 s[30:31], s[8:9]
	s_cbranch_execz .LBB0_525
	s_waitcnt lgkmcnt(0)
	v_lshl_add_u32 v112, v219, 5, s21
	v_mov_b32_e32 v113, v195
	v_lshl_add_u64 v[112:113], v[112:113], 2, s[76:77]
	global_store_dword v[112:113], v114, off

.LBB0_529:
	v_mul_f32_e32 v105, v109, v109
	v_fmac_f32_e32 v105, v108, v108
	v_mul_f32_e32 v108, v111, v111
	v_fmac_f32_e32 v108, v110, v110
	v_add_f32_e32 v105, v105, v108
	v_mul_f32_e32 v108, v113, v113
	v_mul_f32_e32 v107, v107, v107
	v_fmac_f32_e32 v108, v112, v112
	v_fmac_f32_e32 v107, v106, v106
	v_add_f32_e32 v106, v108, v107
	v_add_f32_e32 v105, v105, v106
	v_mul_f32_e32 v106, v101, v101
	v_mul_f32_e32 v107, v103, v103
	v_fmac_f32_e32 v106, v100, v100
	v_fmac_f32_e32 v107, v102, v102
	v_add_f32_e32 v106, v106, v107
	v_mul_f32_e32 v107, v97, v97
	v_mul_f32_e32 v108, v99, v99
	v_fmac_f32_e32 v107, v96, v96
	v_fmac_f32_e32 v108, v98, v98
	v_add_f32_e32 v107, v107, v108
	v_add_f32_e32 v106, v106, v107
	v_add_f32_e32 v105, v105, v106
	v_cvt_pk_bf16_f32 v100, v100, v101
	v_cvt_pk_bf16_f32 v101, v102, v103
	v_cvt_pk_bf16_f32 v102, v96, v97
	v_add_u32_e32 v104, 0x80, v104
	s_waitcnt lgkmcnt(0)
	v_mov_b32_e32 v106, v105
	v_mov_b32_e32 v253, v105
	s_nop 1
	v_permlane16_swap_b32_e32 v106, v253
	v_add_f32_e32 v96, v106, v253
	v_mov_b32_e32 v105, v195
	v_cvt_pk_bf16_f32 v103, v98, v99
	v_lshl_add_u64 v[98:99], v[104:105], 1, s[72:73]
	global_store_dwordx4 v[98:99], v[100:103], off
	v_mov_b32_e32 v97, v96
	v_mov_b32_e32 v253, v96
	s_nop 1
	v_permlane32_swap_b32_e32 v97, v253
	v_add_f32_e32 v98, v97, v253
	s_and_saveexec_b64 s[30:31], s[8:9]
	s_cbranch_execz .LBB0_531
	s_waitcnt lgkmcnt(0)
	v_lshl_add_u32 v96, v114, 5, s21
	v_mov_b32_e32 v97, v195
	v_lshl_add_u64 v[96:97], v[96:97], 2, s[76:77]
	global_store_dword v[96:97], v98, off

.LBB0_535:
	v_mul_f32_e32 v89, v93, v93
	v_fmac_f32_e32 v89, v92, v92
	v_mul_f32_e32 v92, v95, v95
	v_fmac_f32_e32 v92, v94, v94
	v_add_f32_e32 v89, v89, v92
	v_mul_f32_e32 v92, v97, v97
	v_mul_f32_e32 v91, v91, v91
	v_fmac_f32_e32 v92, v96, v96
	v_fmac_f32_e32 v91, v90, v90
	v_add_f32_e32 v90, v92, v91
	v_add_f32_e32 v89, v89, v90
	v_mul_f32_e32 v90, v85, v85
	v_mul_f32_e32 v91, v87, v87
	v_fmac_f32_e32 v90, v84, v84
	v_fmac_f32_e32 v91, v86, v86
	v_add_f32_e32 v90, v90, v91
	v_mul_f32_e32 v91, v81, v81
	v_mul_f32_e32 v92, v83, v83
	v_fmac_f32_e32 v91, v80, v80
	v_fmac_f32_e32 v92, v82, v82
	v_add_f32_e32 v91, v91, v92
	v_add_f32_e32 v90, v90, v91
	v_add_f32_e32 v89, v89, v90
	v_cvt_pk_bf16_f32 v84, v84, v85
	v_cvt_pk_bf16_f32 v85, v86, v87
	v_cvt_pk_bf16_f32 v86, v80, v81
	v_add_u32_e32 v88, 0x80, v88
	s_waitcnt lgkmcnt(0)
	v_mov_b32_e32 v90, v89
	v_mov_b32_e32 v253, v89
	s_nop 1
	v_permlane16_swap_b32_e32 v90, v253
	v_add_f32_e32 v80, v90, v253
	v_mov_b32_e32 v89, v195
	v_cvt_pk_bf16_f32 v87, v82, v83
	v_lshl_add_u64 v[82:83], v[88:89], 1, s[72:73]
	global_store_dwordx4 v[82:83], v[84:87], off
	v_mov_b32_e32 v81, v80
	v_mov_b32_e32 v253, v80
	s_nop 1
	v_permlane32_swap_b32_e32 v81, v253
	v_add_f32_e32 v82, v81, v253
	s_and_saveexec_b64 s[30:31], s[8:9]
	s_cbranch_execz .LBB0_537
	s_waitcnt lgkmcnt(0)
	v_lshl_add_u32 v80, v98, 5, s21
	v_mov_b32_e32 v81, v195
	v_lshl_add_u64 v[80:81], v[80:81], 2, s[76:77]
	global_store_dword v[80:81], v82, off

.LBB0_541:
	v_mul_f32_e32 v73, v77, v77
	v_fmac_f32_e32 v73, v76, v76
	v_mul_f32_e32 v76, v79, v79
	v_fmac_f32_e32 v76, v78, v78
	v_add_f32_e32 v73, v73, v76
	v_mul_f32_e32 v76, v81, v81
	v_mul_f32_e32 v75, v75, v75
	v_fmac_f32_e32 v76, v80, v80
	v_fmac_f32_e32 v75, v74, v74
	v_add_f32_e32 v74, v76, v75
	v_add_f32_e32 v73, v73, v74
	v_mul_f32_e32 v74, v69, v69
	v_mul_f32_e32 v75, v71, v71
	v_fmac_f32_e32 v74, v68, v68
	v_fmac_f32_e32 v75, v70, v70
	v_add_f32_e32 v74, v74, v75
	v_mul_f32_e32 v75, v65, v65
	v_mul_f32_e32 v76, v67, v67
	v_fmac_f32_e32 v75, v64, v64
	v_fmac_f32_e32 v76, v66, v66
	v_add_f32_e32 v75, v75, v76
	v_add_f32_e32 v74, v74, v75
	v_add_f32_e32 v73, v73, v74
	v_cvt_pk_bf16_f32 v68, v68, v69
	v_cvt_pk_bf16_f32 v69, v70, v71
	v_cvt_pk_bf16_f32 v70, v64, v65
	v_add_u32_e32 v72, 0x80, v72
	s_waitcnt lgkmcnt(0)
	v_mov_b32_e32 v74, v73
	v_mov_b32_e32 v253, v73
	s_nop 1
	v_permlane16_swap_b32_e32 v74, v253
	v_add_f32_e32 v64, v74, v253
	v_mov_b32_e32 v73, v195
	v_cvt_pk_bf16_f32 v71, v66, v67
	v_lshl_add_u64 v[66:67], v[72:73], 1, s[72:73]
	global_store_dwordx4 v[66:67], v[68:71], off
	v_mov_b32_e32 v65, v64
	v_mov_b32_e32 v253, v64
	s_nop 1
	v_permlane32_swap_b32_e32 v65, v253
	v_add_f32_e32 v66, v65, v253
	s_and_saveexec_b64 s[30:31], s[8:9]
	s_cbranch_execz .LBB0_543
	s_waitcnt lgkmcnt(0)
	v_lshl_add_u32 v64, v82, 5, s21
	v_mov_b32_e32 v65, v195
	v_lshl_add_u64 v[64:65], v[64:65], 2, s[76:77]
	global_store_dword v[64:65], v66, off

.LBB0_547:
	v_mul_f32_e32 v57, v57, v57
	v_fmac_f32_e32 v57, v56, v56
	v_mul_f32_e32 v56, v59, v59
	v_fmac_f32_e32 v56, v58, v58
	v_add_f32_e32 v56, v57, v56
	v_mul_f32_e32 v57, v53, v53
	v_mul_f32_e32 v58, v55, v55
	v_mul_f32_e32 v61, v61, v61
	v_fmac_f32_e32 v57, v52, v52
	v_fmac_f32_e32 v58, v54, v54
	v_fmac_f32_e32 v61, v60, v60
	v_mul_f32_e32 v60, v63, v63
	v_add_f32_e32 v57, v57, v58
	v_mul_f32_e32 v58, v49, v49
	v_mul_f32_e32 v59, v51, v51
	v_fmac_f32_e32 v60, v62, v62
	v_fmac_f32_e32 v58, v48, v48
	v_fmac_f32_e32 v59, v50, v50
	v_add_f32_e32 v60, v61, v60
	v_add_f32_e32 v58, v58, v59
	v_add_f32_e32 v56, v60, v56
	v_add_f32_e32 v57, v57, v58
	v_add_f32_e32 v58, v56, v57
	v_cvt_pk_bf16_f32 v56, v52, v53
	v_add_u32_e32 v194, 0x80, v194
	v_cvt_pk_bf16_f32 v57, v54, v55
	s_waitcnt lgkmcnt(0)
	v_mov_b32_e32 v59, v58
	v_mov_b32_e32 v253, v58
	s_nop 1
	v_permlane16_swap_b32_e32 v59, v253
	v_add_f32_e32 v52, v59, v253
	v_cvt_pk_bf16_f32 v58, v48, v49
	v_lshl_add_u64 v[48:49], v[194:195], 1, s[72:73]
	v_cvt_pk_bf16_f32 v59, v50, v51
	global_store_dwordx4 v[48:49], v[56:59], off
	v_mov_b32_e32 v53, v52
	v_mov_b32_e32 v253, v52
	s_nop 1
	v_permlane32_swap_b32_e32 v53, v253
	v_add_f32_e32 v50, v53, v253
	s_and_saveexec_b64 s[30:31], s[8:9]
	s_cbranch_execz .LBB0_549
	v_lshl_add_u32 v194, v120, 5, s21
	s_waitcnt lgkmcnt(0)
	v_lshl_add_u64 v[48:49], v[194:195], 2, s[76:77]
	global_store_dword v[48:49], v50, off

.LBB0_553:
	v_mul_f32_e32 v41, v41, v41
	v_fmac_f32_e32 v41, v40, v40
	v_mul_f32_e32 v40, v43, v43
	v_fmac_f32_e32 v40, v42, v42
	v_add_f32_e32 v40, v41, v40
	v_mul_f32_e32 v41, v37, v37
	v_mul_f32_e32 v42, v39, v39
	v_mul_f32_e32 v45, v45, v45
	v_fmac_f32_e32 v41, v36, v36
	v_fmac_f32_e32 v42, v38, v38
	v_fmac_f32_e32 v45, v44, v44
	v_mul_f32_e32 v44, v47, v47
	v_add_f32_e32 v41, v41, v42
	v_mul_f32_e32 v42, v33, v33
	v_mul_f32_e32 v43, v35, v35
	v_fmac_f32_e32 v44, v46, v46
	v_fmac_f32_e32 v42, v32, v32
	v_fmac_f32_e32 v43, v34, v34
	v_add_f32_e32 v44, v45, v44
	v_add_f32_e32 v42, v42, v43
	v_add_f32_e32 v40, v44, v40
	v_add_f32_e32 v41, v41, v42
	v_add_f32_e32 v42, v40, v41
	v_cvt_pk_bf16_f32 v40, v36, v37
	v_add_u32_e32 v194, 0x80, v194
	v_cvt_pk_bf16_f32 v41, v38, v39
	s_waitcnt lgkmcnt(0)
	v_mov_b32_e32 v43, v42
	v_mov_b32_e32 v253, v42
	s_nop 1
	v_permlane16_swap_b32_e32 v43, v253
	v_add_f32_e32 v36, v43, v253
	v_cvt_pk_bf16_f32 v42, v32, v33
	v_lshl_add_u64 v[32:33], v[194:195], 1, s[72:73]
	v_cvt_pk_bf16_f32 v43, v34, v35
	global_store_dwordx4 v[32:33], v[40:43], off
	v_mov_b32_e32 v37, v36
	v_mov_b32_e32 v253, v36
	s_nop 1
	v_permlane32_swap_b32_e32 v37, v253
	v_add_f32_e32 v34, v37, v253
	s_and_saveexec_b64 s[30:31], s[8:9]
	s_cbranch_execz .LBB0_555
	v_lshl_add_u32 v194, v48, 5, s21
	s_waitcnt lgkmcnt(0)
	v_lshl_add_u64 v[32:33], v[194:195], 2, s[76:77]
	global_store_dword v[32:33], v34, off

.LBB0_559:
	v_mul_f32_e32 v25, v25, v25
	v_fmac_f32_e32 v25, v24, v24
	v_mul_f32_e32 v24, v27, v27
	v_fmac_f32_e32 v24, v26, v26
	v_add_f32_e32 v24, v25, v24
	v_mul_f32_e32 v25, v21, v21
	v_mul_f32_e32 v26, v23, v23
	v_mul_f32_e32 v29, v29, v29
	v_fmac_f32_e32 v25, v20, v20
	v_fmac_f32_e32 v26, v22, v22
	v_fmac_f32_e32 v29, v28, v28
	v_mul_f32_e32 v28, v31, v31
	v_add_f32_e32 v25, v25, v26
	v_mul_f32_e32 v26, v17, v17
	v_mul_f32_e32 v27, v19, v19
	v_fmac_f32_e32 v28, v30, v30
	v_fmac_f32_e32 v26, v16, v16
	v_fmac_f32_e32 v27, v18, v18
	v_add_f32_e32 v28, v29, v28
	v_add_f32_e32 v26, v26, v27
	v_add_f32_e32 v24, v28, v24
	v_add_f32_e32 v25, v25, v26
	v_add_f32_e32 v26, v24, v25
	v_cvt_pk_bf16_f32 v24, v20, v21
	v_add_u32_e32 v194, 0x80, v194
	v_cvt_pk_bf16_f32 v25, v22, v23
	s_waitcnt lgkmcnt(0)
	v_mov_b32_e32 v27, v26
	v_mov_b32_e32 v253, v26
	s_nop 1
	v_permlane16_swap_b32_e32 v27, v253
	v_add_f32_e32 v20, v27, v253
	v_cvt_pk_bf16_f32 v26, v16, v17
	v_lshl_add_u64 v[16:17], v[194:195], 1, s[72:73]
	v_cvt_pk_bf16_f32 v27, v18, v19
	global_store_dwordx4 v[16:17], v[24:27], off
	v_mov_b32_e32 v21, v20
	v_mov_b32_e32 v253, v20
	s_nop 1
	v_permlane32_swap_b32_e32 v21, v253
	v_add_f32_e32 v18, v21, v253
	s_and_saveexec_b64 s[30:31], s[8:9]
	s_cbranch_execz .LBB0_561
	v_lshl_add_u32 v194, v32, 5, s21
	s_waitcnt lgkmcnt(0)
	v_lshl_add_u64 v[16:17], v[194:195], 2, s[76:77]
	global_store_dword v[16:17], v18, off

.LBB0_565:
	v_mul_f32_e32 v9, v9, v9
	v_fmac_f32_e32 v9, v8, v8
	v_mul_f32_e32 v8, v11, v11
	v_fmac_f32_e32 v8, v10, v10
	v_add_f32_e32 v8, v9, v8
	v_mul_f32_e32 v9, v5, v5
	v_mul_f32_e32 v10, v7, v7
	v_mul_f32_e32 v13, v13, v13
	v_fmac_f32_e32 v9, v4, v4
	v_fmac_f32_e32 v10, v6, v6
	v_fmac_f32_e32 v13, v12, v12
	v_mul_f32_e32 v12, v15, v15
	v_add_f32_e32 v9, v9, v10
	v_mul_f32_e32 v10, v1, v1
	v_mul_f32_e32 v11, v3, v3
	v_fmac_f32_e32 v12, v14, v14
	v_fmac_f32_e32 v10, v0, v0
	v_fmac_f32_e32 v11, v2, v2
	v_add_f32_e32 v12, v13, v12
	v_add_f32_e32 v10, v10, v11
	v_add_f32_e32 v8, v12, v8
	v_add_f32_e32 v9, v9, v10
	v_add_f32_e32 v10, v8, v9
	v_cvt_pk_bf16_f32 v8, v4, v5
	v_add_u32_e32 v194, 0x80, v194
	v_cvt_pk_bf16_f32 v9, v6, v7
	s_waitcnt lgkmcnt(0)
	v_mov_b32_e32 v11, v10
	v_mov_b32_e32 v253, v10
	s_nop 1
	v_permlane16_swap_b32_e32 v11, v253
	v_add_f32_e32 v4, v11, v253
	v_cvt_pk_bf16_f32 v10, v0, v1
	v_lshl_add_u64 v[0:1], v[194:195], 1, s[72:73]
	v_cvt_pk_bf16_f32 v11, v2, v3
	global_store_dwordx4 v[0:1], v[8:11], off
	v_mov_b32_e32 v5, v4
	v_mov_b32_e32 v253, v4
	s_nop 1
	v_permlane32_swap_b32_e32 v5, v253
	v_add_f32_e32 v2, v5, v253
	s_and_saveexec_b64 s[6:7], s[8:9]
	s_cbranch_execz .LBB0_567
	v_lshl_add_u32 v194, v16, 5, s21
	s_waitcnt lgkmcnt(0)
	v_lshl_add_u64 v[0:1], v[194:195], 2, s[76:77]
	global_store_dword v[0:1], v2, off

.LBB0_717:
	s_lshl_b32 s0, s43, 8
	v_mov_b32_e32 v128, v175
	v_mov_b32_e32 v194, v174
	s_add_i32 s0, s0, s30
	v_mov_b32_e32 v131, v161
	v_add_u32_e32 v181, s0, v128
	s_lshl_b32 s0, s42, 8
	s_or_b32 s0, s0, s31
	v_lshl_add_u32 v170, v194, 3, s0
	v_ashrrev_i32_e32 v171, 31, v170
	v_lshlrev_b32_e32 v160, 11, v181
	v_lshl_add_u64 v[172:173], v[170:171], 1, s[72:73]
	v_lshl_add_u64 v[128:129], v[160:161], 1, v[172:173]
	global_load_dwordx4 v[186:189], v[128:129], off
	global_load_dwordx4 v[190:193], v[128:129], off offset:256
	v_mov_b32_e32 v129, v161
	v_add_u32_e32 v128, 0x8000, v160
	v_add_u32_e32 v130, 0x10000, v160
	v_mov_b32_e32 v133, v161
	v_add_u32_e32 v132, 0x18000, v160
	v_lshl_add_u64 v[128:129], v[128:129], 1, v[172:173]
	v_lshl_add_u64 v[130:131], v[130:131], 1, v[172:173]
	v_lshl_add_u64 v[182:183], v[132:133], 1, v[172:173]
	global_load_dwordx4 v[148:151], v[128:129], off
	global_load_dwordx4 v[144:147], v[128:129], off offset:256
	global_load_dwordx4 v[140:143], v[130:131], off
	global_load_dwordx4 v[136:139], v[130:131], off offset:256
	global_load_dwordx4 v[132:135], v[182:183], off
	s_nop 0
	global_load_dwordx4 v[128:131], v[182:183], off offset:256
	v_and_b32_e32 v182, 64, v180
	v_mov_b32_e32 v183, v161
	v_add_u32_e32 v204, 64, v182
	v_add_u32_e32 v182, v160, v170
	v_cmp_eq_u32_e32 vcc, 0, v194
	v_lshl_add_u64 v[194:195], v[182:183], 1, s[72:73]
	s_lshl_b32 s0, s42, 2
	v_xor_b32_e32 v171, 16, v180
	s_or_b32 s16, s0, s29
	v_cmp_lt_i32_e64 s[0:1], v171, v204
	s_waitcnt vmcnt(0)
	v_lshlrev_b32_e32 v196, 16, v186
	v_and_b32_e32 v197, 0xffff0000, v186
	v_lshlrev_b32_e32 v186, 16, v187
	v_and_b32_e32 v187, 0xffff0000, v187
	v_lshlrev_b32_e32 v198, 16, v188
	v_and_b32_e32 v199, 0xffff0000, v188
	v_lshlrev_b32_e32 v188, 16, v189
	v_and_b32_e32 v189, 0xffff0000, v189
	v_lshlrev_b32_e32 v200, 16, v190
	v_and_b32_e32 v201, 0xffff0000, v190
	v_lshlrev_b32_e32 v190, 16, v191
	v_and_b32_e32 v191, 0xffff0000, v191
	v_lshlrev_b32_e32 v202, 16, v192
	v_and_b32_e32 v203, 0xffff0000, v192
	v_lshlrev_b32_e32 v192, 16, v193
	v_and_b32_e32 v193, 0xffff0000, v193
	v_pk_add_f32 v[126:127], v[126:127], v[186:187]
	v_pk_add_f32 v[124:125], v[124:125], v[196:197]
	v_pk_add_f32 v[122:123], v[122:123], v[188:189]
	v_pk_add_f32 v[120:121], v[120:121], v[198:199]
	v_pk_add_f32 v[118:119], v[118:119], v[190:191]
	v_pk_add_f32 v[116:117], v[116:117], v[200:201]
	v_pk_add_f32 v[186:187], v[114:115], v[192:193]
	v_pk_add_f32 v[188:189], v[112:113], v[202:203]
	v_cvt_pk_bf16_f32 v112, v124, v125
	v_cvt_pk_bf16_f32 v113, v126, v127
	v_cvt_pk_bf16_f32 v114, v120, v121
	v_cvt_pk_bf16_f32 v115, v122, v123
	v_mul_f32_e32 v125, v125, v125
	v_mul_f32_e32 v127, v127, v127
	v_mul_f32_e32 v121, v121, v121
	v_mul_f32_e32 v123, v123, v123
	v_mul_f32_e32 v183, v117, v117
	v_mul_f32_e32 v190, v119, v119
	v_mul_f32_e32 v191, v189, v189
	v_mul_f32_e32 v192, v187, v187
	v_fmac_f32_e32 v125, v124, v124
	v_fmac_f32_e32 v127, v126, v126
	v_fmac_f32_e32 v121, v120, v120
	v_fmac_f32_e32 v123, v122, v122
	v_fmac_f32_e32 v183, v116, v116
	v_fmac_f32_e32 v190, v118, v118
	v_fmac_f32_e32 v191, v188, v188
	v_fmac_f32_e32 v192, v186, v186
	global_store_dwordx4 v[194:195], v[112:115], off
	v_cndmask_b32_e64 v171, v180, v171, s[0:1]
	v_add_u32_e32 v120, 0x80, v182
	v_add_f32_e32 v112, v125, v127
	v_add_f32_e32 v113, v121, v123
	v_add_f32_e32 v114, v183, v190
	v_add_f32_e32 v115, v191, v192
	v_add_f32_e32 v112, v112, v113
	v_add_f32_e32 v113, v114, v115
	v_add_f32_e32 v113, v112, v113
	v_lshlrev_b32_e32 v112, 2, v171
	v_mov_b32_e32 v121, v161
	v_lshl_add_u64 v[120:121], v[120:121], 1, s[72:73]
	v_cvt_pk_bf16_f32 v116, v116, v117
	v_cvt_pk_bf16_f32 v117, v118, v119
	s_waitcnt lgkmcnt(0)
	v_mov_b32_e32 v114, v113
	v_mov_b32_e32 v253, v113
	s_nop 1
	v_permlane16_swap_b32_e32 v114, v253
	v_add_f32_e32 v114, v114, v253
	v_xor_b32_e32 v113, 32, v180
	v_cmp_lt_i32_e64 s[0:1], v113, v204
	v_cvt_pk_bf16_f32 v118, v188, v189
	v_cvt_pk_bf16_f32 v119, v186, v187
	global_store_dwordx4 v[120:121], v[116:119], off
	s_nop 0
	v_cndmask_b32_e64 v113, v180, v113, s[0:1]
	v_lshlrev_b32_e32 v113, 2, v113
	v_mov_b32_e32 v115, v114
	v_mov_b32_e32 v253, v114
	s_nop 1
	v_permlane32_swap_b32_e32 v115, v253
	v_add_f32_e32 v116, v115, v253
	s_and_saveexec_b64 s[0:1], vcc
	s_cbranch_execz .LBB0_719
	s_waitcnt lgkmcnt(0)
	v_lshl_add_u32 v114, v181, 5, s16
	v_mov_b32_e32 v115, v161
	v_lshl_add_u64 v[114:115], v[114:115], 2, s[76:77]
	global_store_dword v[114:115], v116, off
.LBB0_719:
	s_or_b64 exec, exec, s[0:1]
	v_add_u32_e32 v114, 16, v181
	v_lshl_add_u32 v116, v114, 11, v170
	v_lshlrev_b32_e32 v118, 16, v148
	v_and_b32_e32 v119, 0xffff0000, v148
	v_lshlrev_b32_e32 v120, 16, v149
	v_and_b32_e32 v121, 0xffff0000, v149
	v_lshlrev_b32_e32 v122, 16, v150
	v_and_b32_e32 v123, 0xffff0000, v150
	v_mov_b32_e32 v117, v161
	v_lshlrev_b32_e32 v124, 16, v151
	v_and_b32_e32 v125, 0xffff0000, v151
	v_pk_add_f32 v[110:111], v[110:111], v[120:121]
	v_pk_add_f32 v[108:109], v[108:109], v[118:119]
	v_pk_add_f32 v[120:121], v[104:105], v[122:123]
	v_cvt_pk_bf16_f32 v104, v108, v109
	v_cvt_pk_bf16_f32 v105, v110, v111
	v_lshl_add_u64 v[122:123], v[116:117], 1, s[72:73]
	v_pk_add_f32 v[118:119], v[106:107], v[124:125]
	v_cvt_pk_bf16_f32 v106, v120, v121
	s_nop 0
	v_cvt_pk_bf16_f32 v107, v118, v119
	global_store_dwordx4 v[122:123], v[104:107], off
	s_nop 1
	v_mul_f32_e32 v104, v109, v109
	v_mul_f32_e32 v105, v111, v111
	v_fmac_f32_e32 v104, v108, v108
	v_fmac_f32_e32 v105, v110, v110
	v_add_f32_e32 v104, v104, v105
	v_mul_f32_e32 v105, v121, v121
	v_mul_f32_e32 v106, v119, v119
	v_fmac_f32_e32 v105, v120, v120
	v_fmac_f32_e32 v106, v118, v118
	v_add_f32_e32 v105, v105, v106
	s_waitcnt lgkmcnt(0)
	v_add_f32_e32 v115, v104, v105
	v_lshlrev_b32_e32 v104, 16, v144
	v_and_b32_e32 v105, 0xffff0000, v144
	v_lshlrev_b32_e32 v106, 16, v145
	v_and_b32_e32 v107, 0xffff0000, v145
	v_lshlrev_b32_e32 v110, 16, v147
	v_and_b32_e32 v111, 0xffff0000, v147
	v_pk_add_f32 v[102:103], v[102:103], v[106:107]
	v_pk_add_f32 v[100:101], v[100:101], v[104:105]
	v_lshlrev_b32_e32 v108, 16, v146
	v_and_b32_e32 v109, 0xffff0000, v146
	v_pk_add_f32 v[104:105], v[98:99], v[110:111]
	v_mul_f32_e32 v98, v101, v101
	v_mul_f32_e32 v99, v103, v103
	v_pk_add_f32 v[96:97], v[96:97], v[108:109]
	v_fmac_f32_e32 v98, v100, v100
	v_fmac_f32_e32 v99, v102, v102
	v_add_f32_e32 v98, v98, v99
	v_mul_f32_e32 v99, v97, v97
	v_mul_f32_e32 v106, v105, v105
	v_fmac_f32_e32 v99, v96, v96
	v_fmac_f32_e32 v106, v104, v104
	v_add_f32_e32 v99, v99, v106
	v_add_f32_e32 v98, v98, v99
	v_add_f32_e32 v107, v115, v98
	v_cvt_pk_bf16_f32 v98, v100, v101
	v_cvt_pk_bf16_f32 v99, v102, v103
	v_cvt_pk_bf16_f32 v100, v96, v97
	v_add_u32_e32 v106, 0x80, v116
	s_waitcnt lgkmcnt(0)
	v_mov_b32_e32 v108, v107
	v_mov_b32_e32 v253, v107
	s_nop 1
	v_permlane16_swap_b32_e32 v108, v253
	v_add_f32_e32 v96, v108, v253
	v_mov_b32_e32 v107, v161
	v_lshl_add_u64 v[102:103], v[106:107], 1, s[72:73]
	v_cvt_pk_bf16_f32 v101, v104, v105
	global_store_dwordx4 v[102:103], v[98:101], off
	v_mov_b32_e32 v97, v96
	v_mov_b32_e32 v253, v96
	s_nop 1
	v_permlane32_swap_b32_e32 v97, v253
	v_add_f32_e32 v98, v97, v253
	s_and_saveexec_b64 s[0:1], vcc
	s_cbranch_execz .LBB0_721
	s_waitcnt lgkmcnt(0)
	v_lshl_add_u32 v96, v114, 5, s16
	v_mov_b32_e32 v97, v161
	v_lshl_add_u64 v[96:97], v[96:97], 2, s[76:77]
	global_store_dword v[96:97], v98, off
.LBB0_721:
	s_or_b64 exec, exec, s[0:1]
	v_add_u32_e32 v96, 32, v181
	v_lshl_add_u32 v98, v96, 11, v170
	v_lshlrev_b32_e32 v100, 16, v140
	v_and_b32_e32 v101, 0xffff0000, v140
	v_lshlrev_b32_e32 v102, 16, v141
	v_and_b32_e32 v103, 0xffff0000, v141
	v_lshlrev_b32_e32 v104, 16, v142
	v_and_b32_e32 v105, 0xffff0000, v142
	v_mov_b32_e32 v99, v161
	v_lshlrev_b32_e32 v106, 16, v143
	v_and_b32_e32 v107, 0xffff0000, v143
	v_pk_add_f32 v[94:95], v[94:95], v[102:103]
	v_pk_add_f32 v[92:93], v[92:93], v[100:101]
	v_pk_add_f32 v[102:103], v[88:89], v[104:105]
	v_cvt_pk_bf16_f32 v88, v92, v93
	v_cvt_pk_bf16_f32 v89, v94, v95
	v_lshl_add_u64 v[104:105], v[98:99], 1, s[72:73]
	v_pk_add_f32 v[100:101], v[90:91], v[106:107]
	v_cvt_pk_bf16_f32 v90, v102, v103
	s_nop 0
	v_cvt_pk_bf16_f32 v91, v100, v101
	global_store_dwordx4 v[104:105], v[88:91], off
	s_nop 1
	v_mul_f32_e32 v88, v93, v93
	v_mul_f32_e32 v89, v95, v95
	v_fmac_f32_e32 v88, v92, v92
	v_fmac_f32_e32 v89, v94, v94
	v_add_f32_e32 v88, v88, v89
	v_mul_f32_e32 v89, v103, v103
	v_mul_f32_e32 v90, v101, v101
	v_fmac_f32_e32 v89, v102, v102
	v_fmac_f32_e32 v90, v100, v100
	v_add_f32_e32 v89, v89, v90
	s_waitcnt lgkmcnt(0)
	v_add_f32_e32 v97, v88, v89
	v_lshlrev_b32_e32 v88, 16, v136
	v_and_b32_e32 v89, 0xffff0000, v136
	v_lshlrev_b32_e32 v90, 16, v137
	v_and_b32_e32 v91, 0xffff0000, v137
	v_lshlrev_b32_e32 v94, 16, v139
	v_and_b32_e32 v95, 0xffff0000, v139
	v_pk_add_f32 v[86:87], v[86:87], v[90:91]
	v_pk_add_f32 v[84:85], v[84:85], v[88:89]
	v_lshlrev_b32_e32 v92, 16, v138
	v_and_b32_e32 v93, 0xffff0000, v138
	v_pk_add_f32 v[88:89], v[82:83], v[94:95]
	v_mul_f32_e32 v82, v85, v85
	v_mul_f32_e32 v83, v87, v87
	v_pk_add_f32 v[80:81], v[80:81], v[92:93]
	v_fmac_f32_e32 v82, v84, v84
	v_fmac_f32_e32 v83, v86, v86
	v_add_f32_e32 v82, v82, v83
	v_mul_f32_e32 v83, v81, v81
	v_mul_f32_e32 v90, v89, v89
	v_fmac_f32_e32 v83, v80, v80
	v_fmac_f32_e32 v90, v88, v88
	v_add_f32_e32 v83, v83, v90
	v_add_f32_e32 v82, v82, v83
	v_add_f32_e32 v91, v97, v82
	v_cvt_pk_bf16_f32 v82, v84, v85
	v_cvt_pk_bf16_f32 v83, v86, v87
	v_cvt_pk_bf16_f32 v84, v80, v81
	v_add_u32_e32 v90, 0x80, v98
	s_waitcnt lgkmcnt(0)
	v_mov_b32_e32 v92, v91
	v_mov_b32_e32 v253, v91
	s_nop 1
	v_permlane16_swap_b32_e32 v92, v253
	v_add_f32_e32 v80, v92, v253
	v_mov_b32_e32 v91, v161
	v_lshl_add_u64 v[86:87], v[90:91], 1, s[72:73]
	v_cvt_pk_bf16_f32 v85, v88, v89
	global_store_dwordx4 v[86:87], v[82:85], off
	v_mov_b32_e32 v81, v80
	v_mov_b32_e32 v253, v80
	s_nop 1
	v_permlane32_swap_b32_e32 v81, v253
	v_add_f32_e32 v82, v81, v253
	s_and_saveexec_b64 s[0:1], vcc
	s_cbranch_execz .LBB0_723
	s_waitcnt lgkmcnt(0)
	v_lshl_add_u32 v80, v96, 5, s16
	v_mov_b32_e32 v81, v161
	v_lshl_add_u64 v[80:81], v[80:81], 2, s[76:77]
	global_store_dword v[80:81], v82, off
.LBB0_723:
	s_or_b64 exec, exec, s[0:1]
	v_add_u32_e32 v80, 48, v181
	v_lshl_add_u32 v82, v80, 11, v170
	v_lshlrev_b32_e32 v84, 16, v132
	v_and_b32_e32 v85, 0xffff0000, v132
	v_lshlrev_b32_e32 v86, 16, v133
	v_and_b32_e32 v87, 0xffff0000, v133
	v_lshlrev_b32_e32 v88, 16, v134
	v_and_b32_e32 v89, 0xffff0000, v134
	v_mov_b32_e32 v83, v161
	v_lshlrev_b32_e32 v90, 16, v135
	v_and_b32_e32 v91, 0xffff0000, v135
	v_pk_add_f32 v[78:79], v[78:79], v[86:87]
	v_pk_add_f32 v[76:77], v[76:77], v[84:85]
	v_pk_add_f32 v[86:87], v[72:73], v[88:89]
	v_cvt_pk_bf16_f32 v72, v76, v77
	v_cvt_pk_bf16_f32 v73, v78, v79
	v_lshl_add_u64 v[88:89], v[82:83], 1, s[72:73]
	v_pk_add_f32 v[84:85], v[74:75], v[90:91]
	v_cvt_pk_bf16_f32 v74, v86, v87
	s_nop 0
	v_cvt_pk_bf16_f32 v75, v84, v85
	global_store_dwordx4 v[88:89], v[72:75], off
	s_nop 1
	v_mul_f32_e32 v72, v77, v77
	v_mul_f32_e32 v73, v79, v79
	v_fmac_f32_e32 v72, v76, v76
	v_fmac_f32_e32 v73, v78, v78
	v_add_f32_e32 v72, v72, v73
	v_mul_f32_e32 v73, v87, v87
	v_mul_f32_e32 v74, v85, v85
	v_fmac_f32_e32 v73, v86, v86
	v_fmac_f32_e32 v74, v84, v84
	v_add_f32_e32 v73, v73, v74
	s_waitcnt lgkmcnt(0)
	v_add_f32_e32 v81, v72, v73
	v_lshlrev_b32_e32 v72, 16, v128
	v_and_b32_e32 v73, 0xffff0000, v128
	v_lshlrev_b32_e32 v74, 16, v129
	v_and_b32_e32 v75, 0xffff0000, v129
	v_lshlrev_b32_e32 v78, 16, v131
	v_and_b32_e32 v79, 0xffff0000, v131
	v_pk_add_f32 v[70:71], v[70:71], v[74:75]
	v_pk_add_f32 v[68:69], v[68:69], v[72:73]
	v_lshlrev_b32_e32 v76, 16, v130
	v_and_b32_e32 v77, 0xffff0000, v130
	v_pk_add_f32 v[72:73], v[66:67], v[78:79]
	v_mul_f32_e32 v66, v69, v69
	v_mul_f32_e32 v67, v71, v71
	v_pk_add_f32 v[64:65], v[64:65], v[76:77]
	v_fmac_f32_e32 v66, v68, v68
	v_fmac_f32_e32 v67, v70, v70
	v_add_f32_e32 v66, v66, v67
	v_mul_f32_e32 v67, v65, v65
	v_mul_f32_e32 v74, v73, v73
	v_fmac_f32_e32 v67, v64, v64
	v_fmac_f32_e32 v74, v72, v72
	v_add_f32_e32 v67, v67, v74
	v_add_f32_e32 v66, v66, v67
	v_add_f32_e32 v75, v81, v66
	v_cvt_pk_bf16_f32 v66, v68, v69
	v_cvt_pk_bf16_f32 v67, v70, v71
	v_cvt_pk_bf16_f32 v68, v64, v65
	v_add_u32_e32 v74, 0x80, v82
	s_waitcnt lgkmcnt(0)
	v_mov_b32_e32 v76, v75
	v_mov_b32_e32 v253, v75
	s_nop 1
	v_permlane16_swap_b32_e32 v76, v253
	v_add_f32_e32 v64, v76, v253
	v_mov_b32_e32 v75, v161
	v_lshl_add_u64 v[70:71], v[74:75], 1, s[72:73]
	v_cvt_pk_bf16_f32 v69, v72, v73
	global_store_dwordx4 v[70:71], v[66:69], off
	v_mov_b32_e32 v65, v64
	v_mov_b32_e32 v253, v64
	s_nop 1
	v_permlane32_swap_b32_e32 v65, v253
	v_add_f32_e32 v66, v65, v253
	s_and_saveexec_b64 s[0:1], vcc
	s_cbranch_execz .LBB0_725
	s_waitcnt lgkmcnt(0)
	v_lshl_add_u32 v64, v80, 5, s16
	v_mov_b32_e32 v65, v161
	v_lshl_add_u64 v[64:65], v[64:65], 2, s[76:77]
	global_store_dword v[64:65], v66, off
.LBB0_725:
	s_or_b64 exec, exec, s[0:1]
	v_add_u32_e32 v64, 0x40000, v160
	s_waitcnt lgkmcnt(0)
	v_mov_b32_e32 v65, v161
	v_lshl_add_u64 v[64:65], v[64:65], 1, v[172:173]
	global_load_dwordx4 v[90:93], v[64:65], off
	global_load_dwordx4 v[94:97], v[64:65], off offset:256
	v_add_u32_e32 v64, 0x48000, v160
	v_mov_b32_e32 v65, v161
	v_add_u32_e32 v66, 0x50000, v160
	v_mov_b32_e32 v67, v161
	v_add_u32_e32 v160, 0x58000, v160
	v_lshl_add_u64 v[64:65], v[64:65], 1, v[172:173]
	v_lshl_add_u64 v[66:67], v[66:67], 1, v[172:173]
	v_lshl_add_u64 v[88:89], v[160:161], 1, v[172:173]
	global_load_dwordx4 v[84:87], v[64:65], off
	global_load_dwordx4 v[80:83], v[64:65], off offset:256
	global_load_dwordx4 v[76:79], v[66:67], off
	global_load_dwordx4 v[72:75], v[66:67], off offset:256
	global_load_dwordx4 v[68:71], v[88:89], off
	s_nop 0
	global_load_dwordx4 v[64:67], v[88:89], off offset:256
	v_add_u32_e32 v88, 0x80, v181
	v_lshl_add_u32 v160, v88, 11, v170
	v_lshl_add_u64 v[98:99], v[160:161], 1, s[72:73]
	v_add_u32_e32 v160, 0x80, v160
	s_waitcnt vmcnt(7)
	v_lshlrev_b32_e32 v100, 16, v90
	v_and_b32_e32 v101, 0xffff0000, v90
	v_lshlrev_b32_e32 v90, 16, v91
	v_and_b32_e32 v91, 0xffff0000, v91
	v_lshlrev_b32_e32 v102, 16, v92
	v_and_b32_e32 v103, 0xffff0000, v92
	v_lshlrev_b32_e32 v92, 16, v93
	v_and_b32_e32 v93, 0xffff0000, v93
	s_waitcnt vmcnt(6)
	v_lshlrev_b32_e32 v104, 16, v94
	v_and_b32_e32 v105, 0xffff0000, v94
	v_lshlrev_b32_e32 v94, 16, v95
	v_and_b32_e32 v95, 0xffff0000, v95
	v_lshlrev_b32_e32 v106, 16, v96
	v_and_b32_e32 v107, 0xffff0000, v96
	v_lshlrev_b32_e32 v96, 16, v97
	v_and_b32_e32 v97, 0xffff0000, v97
	v_pk_add_f32 v[62:63], v[62:63], v[90:91]
	v_pk_add_f32 v[60:61], v[60:61], v[100:101]
	v_pk_add_f32 v[58:59], v[58:59], v[92:93]
	v_pk_add_f32 v[56:57], v[56:57], v[102:103]
	v_pk_add_f32 v[54:55], v[54:55], v[94:95]
	v_pk_add_f32 v[52:53], v[52:53], v[104:105]
	v_pk_add_f32 v[90:91], v[50:51], v[96:97]
	v_pk_add_f32 v[92:93], v[48:49], v[106:107]
	v_cvt_pk_bf16_f32 v48, v60, v61
	v_cvt_pk_bf16_f32 v49, v62, v63
	v_cvt_pk_bf16_f32 v50, v56, v57
	v_cvt_pk_bf16_f32 v51, v58, v59
	v_mul_f32_e32 v61, v61, v61
	v_mul_f32_e32 v63, v63, v63
	v_mul_f32_e32 v57, v57, v57
	v_mul_f32_e32 v59, v59, v59
	v_mul_f32_e32 v89, v53, v53
	v_mul_f32_e32 v94, v55, v55
	v_mul_f32_e32 v95, v93, v93
	v_mul_f32_e32 v96, v91, v91
	v_fmac_f32_e32 v61, v60, v60
	v_fmac_f32_e32 v63, v62, v62
	v_fmac_f32_e32 v57, v56, v56
	v_fmac_f32_e32 v59, v58, v58
	v_fmac_f32_e32 v89, v52, v52
	v_fmac_f32_e32 v94, v54, v54
	v_fmac_f32_e32 v95, v92, v92
	v_fmac_f32_e32 v96, v90, v90
	v_add_f32_e32 v56, v61, v63
	v_add_f32_e32 v57, v57, v59
	v_add_f32_e32 v58, v89, v94
	v_add_f32_e32 v59, v95, v96
	v_add_f32_e32 v56, v56, v57
	v_add_f32_e32 v57, v58, v59
	v_add_f32_e32 v56, v56, v57
	global_store_dwordx4 v[98:99], v[48:51], off
	s_nop 1
	v_cvt_pk_bf16_f32 v50, v52, v53
	s_waitcnt lgkmcnt(0)
	v_mov_b32_e32 v57, v56
	v_mov_b32_e32 v253, v56
	s_nop 1
	v_permlane16_swap_b32_e32 v57, v253
	v_add_f32_e32 v48, v57, v253
	v_cvt_pk_bf16_f32 v51, v54, v55
	v_lshl_add_u64 v[54:55], v[160:161], 1, s[72:73]
	v_cvt_pk_bf16_f32 v52, v92, v93
	v_cvt_pk_bf16_f32 v53, v90, v91
	global_store_dwordx4 v[54:55], v[50:53], off
	v_mov_b32_e32 v49, v48
	v_mov_b32_e32 v253, v48
	s_nop 1
	v_permlane32_swap_b32_e32 v49, v253
	v_add_f32_e32 v50, v49, v253
	s_and_saveexec_b64 s[0:1], vcc
	s_cbranch_execz .LBB0_727
	v_lshl_add_u32 v160, v88, 5, s16
	s_waitcnt lgkmcnt(0)
	v_lshl_add_u64 v[48:49], v[160:161], 2, s[76:77]
	global_store_dword v[48:49], v50, off
.LBB0_727:
	s_or_b64 exec, exec, s[0:1]
	s_waitcnt vmcnt(7)
	v_lshlrev_b32_e32 v50, 16, v84
	v_and_b32_e32 v51, 0xffff0000, v84
	v_lshlrev_b32_e32 v52, 16, v85
	v_and_b32_e32 v53, 0xffff0000, v85
	v_lshlrev_b32_e32 v54, 16, v86
	v_and_b32_e32 v55, 0xffff0000, v86
	v_pk_add_f32 v[44:45], v[44:45], v[50:51]
	v_pk_add_f32 v[46:47], v[46:47], v[52:53]
	v_pk_add_f32 v[52:53], v[40:41], v[54:55]
	v_cvt_pk_bf16_f32 v40, v44, v45
	v_mul_f32_e32 v45, v45, v45
	v_lshlrev_b32_e32 v56, 16, v87
	v_and_b32_e32 v57, 0xffff0000, v87
	v_fmac_f32_e32 v45, v44, v44
	v_mul_f32_e32 v44, v47, v47
	v_pk_add_f32 v[50:51], v[42:43], v[56:57]
	v_fmac_f32_e32 v44, v46, v46
	v_cvt_pk_bf16_f32 v41, v46, v47
	v_add_f32_e32 v44, v45, v44
	v_mul_f32_e32 v45, v53, v53
	v_mul_f32_e32 v46, v51, v51
	v_fmac_f32_e32 v45, v52, v52
	v_fmac_f32_e32 v46, v50, v50
	v_add_f32_e32 v45, v45, v46
	s_waitcnt lgkmcnt(0)
	v_add_f32_e32 v49, v44, v45
	s_waitcnt vmcnt(6)
	v_lshlrev_b32_e32 v44, 16, v80
	v_and_b32_e32 v45, 0xffff0000, v80
	v_lshlrev_b32_e32 v46, 16, v81
	v_and_b32_e32 v47, 0xffff0000, v81
	v_cvt_pk_bf16_f32 v42, v52, v53
	v_cvt_pk_bf16_f32 v43, v50, v51
	v_lshlrev_b32_e32 v50, 16, v82
	v_and_b32_e32 v51, 0xffff0000, v82
	v_pk_add_f32 v[38:39], v[38:39], v[46:47]
	v_pk_add_f32 v[36:37], v[36:37], v[44:45]
	v_lshlrev_b32_e32 v52, 16, v83
	v_and_b32_e32 v53, 0xffff0000, v83
	v_pk_add_f32 v[46:47], v[32:33], v[50:51]
	v_mul_f32_e32 v32, v37, v37
	v_mul_f32_e32 v33, v39, v39
	v_pk_add_f32 v[44:45], v[34:35], v[52:53]
	v_fmac_f32_e32 v32, v36, v36
	v_fmac_f32_e32 v33, v38, v38
	v_add_f32_e32 v32, v32, v33
	v_mul_f32_e32 v33, v47, v47
	v_mul_f32_e32 v34, v45, v45
	v_fmac_f32_e32 v33, v46, v46
	v_fmac_f32_e32 v34, v44, v44
	v_add_f32_e32 v33, v33, v34
	v_add_f32_e32 v32, v32, v33
	v_add_f32_e32 v32, v49, v32
	v_add_u32_e32 v48, 0x90, v181
	v_lshl_add_u32 v160, v48, 11, v170
	v_lshl_add_u64 v[54:55], v[160:161], 1, s[72:73]
	v_add_u32_e32 v160, 0x80, v160
	s_waitcnt lgkmcnt(0)
	v_mov_b32_e32 v33, v32
	v_mov_b32_e32 v253, v32
	s_nop 1
	v_permlane16_swap_b32_e32 v33, v253
	v_add_f32_e32 v32, v33, v253
	global_store_dwordx4 v[54:55], v[40:43], off
	v_cvt_pk_bf16_f32 v34, v36, v37
	v_cvt_pk_bf16_f32 v35, v38, v39
	v_lshl_add_u64 v[38:39], v[160:161], 1, s[72:73]
	v_cvt_pk_bf16_f32 v36, v46, v47
	v_cvt_pk_bf16_f32 v37, v44, v45
	global_store_dwordx4 v[38:39], v[34:37], off
	v_mov_b32_e32 v33, v32
	v_mov_b32_e32 v253, v32
	s_nop 1
	v_permlane32_swap_b32_e32 v33, v253
	v_add_f32_e32 v34, v33, v253
	s_and_saveexec_b64 s[0:1], vcc
	s_cbranch_execz .LBB0_729
	v_lshl_add_u32 v160, v48, 5, s16
	s_waitcnt lgkmcnt(0)
	v_lshl_add_u64 v[32:33], v[160:161], 2, s[76:77]
	global_store_dword v[32:33], v34, off
.LBB0_729:
	s_or_b64 exec, exec, s[0:1]
	s_waitcnt vmcnt(7)
	v_lshlrev_b32_e32 v34, 16, v76
	v_and_b32_e32 v35, 0xffff0000, v76
	v_lshlrev_b32_e32 v36, 16, v77
	v_and_b32_e32 v37, 0xffff0000, v77
	v_lshlrev_b32_e32 v38, 16, v78
	v_and_b32_e32 v39, 0xffff0000, v78
	v_pk_add_f32 v[28:29], v[28:29], v[34:35]
	v_pk_add_f32 v[30:31], v[30:31], v[36:37]
	v_pk_add_f32 v[36:37], v[24:25], v[38:39]
	v_cvt_pk_bf16_f32 v24, v28, v29
	v_mul_f32_e32 v29, v29, v29
	v_lshlrev_b32_e32 v40, 16, v79
	v_and_b32_e32 v41, 0xffff0000, v79
	v_fmac_f32_e32 v29, v28, v28
	v_mul_f32_e32 v28, v31, v31
	v_pk_add_f32 v[34:35], v[26:27], v[40:41]
	v_fmac_f32_e32 v28, v30, v30
	v_cvt_pk_bf16_f32 v25, v30, v31
	v_add_f32_e32 v28, v29, v28
	v_mul_f32_e32 v29, v37, v37
	v_mul_f32_e32 v30, v35, v35
	v_fmac_f32_e32 v29, v36, v36
	v_fmac_f32_e32 v30, v34, v34
	v_add_f32_e32 v29, v29, v30
	s_waitcnt lgkmcnt(0)
	v_add_f32_e32 v33, v28, v29
	s_waitcnt vmcnt(6)
	v_lshlrev_b32_e32 v28, 16, v72
	v_and_b32_e32 v29, 0xffff0000, v72
	v_lshlrev_b32_e32 v30, 16, v73
	v_and_b32_e32 v31, 0xffff0000, v73
	v_cvt_pk_bf16_f32 v26, v36, v37
	v_cvt_pk_bf16_f32 v27, v34, v35
	v_lshlrev_b32_e32 v34, 16, v74
	v_and_b32_e32 v35, 0xffff0000, v74
	v_pk_add_f32 v[22:23], v[22:23], v[30:31]
	v_pk_add_f32 v[20:21], v[20:21], v[28:29]
	v_lshlrev_b32_e32 v36, 16, v75
	v_and_b32_e32 v37, 0xffff0000, v75
	v_pk_add_f32 v[30:31], v[16:17], v[34:35]
	v_mul_f32_e32 v16, v21, v21
	v_mul_f32_e32 v17, v23, v23
	v_pk_add_f32 v[28:29], v[18:19], v[36:37]
	v_fmac_f32_e32 v16, v20, v20
	v_fmac_f32_e32 v17, v22, v22
	v_add_f32_e32 v16, v16, v17
	v_mul_f32_e32 v17, v31, v31
	v_mul_f32_e32 v18, v29, v29
	v_fmac_f32_e32 v17, v30, v30
	v_fmac_f32_e32 v18, v28, v28
	v_add_f32_e32 v17, v17, v18
	v_add_f32_e32 v16, v16, v17
	v_add_f32_e32 v16, v33, v16
	v_add_u32_e32 v32, 0xa0, v181
	v_lshl_add_u32 v160, v32, 11, v170
	v_lshl_add_u64 v[38:39], v[160:161], 1, s[72:73]
	v_add_u32_e32 v160, 0x80, v160
	s_waitcnt lgkmcnt(0)
	v_mov_b32_e32 v17, v16
	v_mov_b32_e32 v253, v16
	s_nop 1
	v_permlane16_swap_b32_e32 v17, v253
	v_add_f32_e32 v16, v17, v253
	global_store_dwordx4 v[38:39], v[24:27], off
	v_cvt_pk_bf16_f32 v18, v20, v21
	v_cvt_pk_bf16_f32 v19, v22, v23
	v_lshl_add_u64 v[22:23], v[160:161], 1, s[72:73]
	v_cvt_pk_bf16_f32 v20, v30, v31
	v_cvt_pk_bf16_f32 v21, v28, v29
	global_store_dwordx4 v[22:23], v[18:21], off
	v_mov_b32_e32 v17, v16
	v_mov_b32_e32 v253, v16
	s_nop 1
	v_permlane32_swap_b32_e32 v17, v253
	v_add_f32_e32 v18, v17, v253
	s_and_saveexec_b64 s[0:1], vcc
	s_cbranch_execz .LBB0_731
	v_lshl_add_u32 v160, v32, 5, s16
	s_waitcnt lgkmcnt(0)
	v_lshl_add_u64 v[16:17], v[160:161], 2, s[76:77]
	global_store_dword v[16:17], v18, off
.LBB0_731:
	s_or_b64 exec, exec, s[0:1]
	s_waitcnt vmcnt(7)
	v_lshlrev_b32_e32 v18, 16, v68
	v_and_b32_e32 v19, 0xffff0000, v68
	v_lshlrev_b32_e32 v20, 16, v69
	v_and_b32_e32 v21, 0xffff0000, v69
	v_lshlrev_b32_e32 v22, 16, v70
	v_and_b32_e32 v23, 0xffff0000, v70
	v_pk_add_f32 v[12:13], v[12:13], v[18:19]
	v_pk_add_f32 v[14:15], v[14:15], v[20:21]
	v_pk_add_f32 v[20:21], v[8:9], v[22:23]
	v_cvt_pk_bf16_f32 v8, v12, v13
	v_mul_f32_e32 v13, v13, v13
	v_lshlrev_b32_e32 v24, 16, v71
	v_and_b32_e32 v25, 0xffff0000, v71
	v_fmac_f32_e32 v13, v12, v12
	v_mul_f32_e32 v12, v15, v15
	v_pk_add_f32 v[18:19], v[10:11], v[24:25]
	v_fmac_f32_e32 v12, v14, v14
	v_cvt_pk_bf16_f32 v9, v14, v15
	v_add_f32_e32 v12, v13, v12
	v_mul_f32_e32 v13, v21, v21
	v_mul_f32_e32 v14, v19, v19
	v_fmac_f32_e32 v13, v20, v20
	v_fmac_f32_e32 v14, v18, v18
	v_add_f32_e32 v13, v13, v14
	s_waitcnt lgkmcnt(0)
	v_add_f32_e32 v17, v12, v13
	s_waitcnt vmcnt(6)
	v_lshlrev_b32_e32 v12, 16, v64
	v_and_b32_e32 v13, 0xffff0000, v64
	v_lshlrev_b32_e32 v14, 16, v65
	v_and_b32_e32 v15, 0xffff0000, v65
	v_cvt_pk_bf16_f32 v10, v20, v21
	v_cvt_pk_bf16_f32 v11, v18, v19
	v_lshlrev_b32_e32 v18, 16, v66
	v_and_b32_e32 v19, 0xffff0000, v66
	v_pk_add_f32 v[6:7], v[6:7], v[14:15]
	v_pk_add_f32 v[4:5], v[4:5], v[12:13]
	v_lshlrev_b32_e32 v20, 16, v67
	v_and_b32_e32 v21, 0xffff0000, v67
	v_pk_add_f32 v[14:15], v[0:1], v[18:19]
	v_mul_f32_e32 v0, v5, v5
	v_mul_f32_e32 v1, v7, v7
	v_pk_add_f32 v[12:13], v[2:3], v[20:21]
	v_fmac_f32_e32 v0, v4, v4
	v_fmac_f32_e32 v1, v6, v6
	v_add_f32_e32 v0, v0, v1
	v_mul_f32_e32 v1, v15, v15
	v_mul_f32_e32 v2, v13, v13
	v_fmac_f32_e32 v1, v14, v14
	v_fmac_f32_e32 v2, v12, v12
	v_add_f32_e32 v1, v1, v2
	v_add_f32_e32 v0, v0, v1
	v_add_f32_e32 v0, v17, v0
	v_add_u32_e32 v16, 0xb0, v181
	v_lshl_add_u32 v160, v16, 11, v170
	v_lshl_add_u64 v[22:23], v[160:161], 1, s[72:73]
	v_add_u32_e32 v160, 0x80, v160
	s_waitcnt lgkmcnt(0)
	v_mov_b32_e32 v1, v0
	v_mov_b32_e32 v253, v0
	s_nop 1
	v_permlane16_swap_b32_e32 v1, v253
	v_add_f32_e32 v0, v1, v253
	global_store_dwordx4 v[22:23], v[8:11], off
	v_cvt_pk_bf16_f32 v2, v4, v5
	v_cvt_pk_bf16_f32 v3, v6, v7
	v_lshl_add_u64 v[6:7], v[160:161], 1, s[72:73]
	v_cvt_pk_bf16_f32 v4, v14, v15
	v_cvt_pk_bf16_f32 v5, v12, v13
	global_store_dwordx4 v[6:7], v[2:5], off
	v_mov_b32_e32 v1, v0
	v_mov_b32_e32 v253, v0
	s_nop 1
	v_permlane32_swap_b32_e32 v1, v253
	v_add_f32_e32 v2, v1, v253
	s_and_saveexec_b64 s[0:1], vcc
	s_cbranch_execz .LBB0_733
	v_lshl_add_u32 v160, v16, 5, s16
	s_waitcnt lgkmcnt(0)
	v_lshl_add_u64 v[0:1], v[160:161], 2, s[76:77]
	global_store_dword v[0:1], v2, off

.LBB0_1283:
	s_lshl_b32 s1, s20, 8
	v_mov_b32_e32 v128, v175
	v_mov_b32_e32 v194, v174
	s_add_i32 s1, s1, s35
	v_mov_b32_e32 v131, v161
	v_add_u32_e32 v181, s1, v128
	s_lshl_b32 s1, s0, 8
	s_or_b32 s1, s1, s36
	v_lshl_add_u32 v170, v194, 3, s1
	v_ashrrev_i32_e32 v171, 31, v170
	v_lshlrev_b32_e32 v160, 11, v181
	v_lshl_add_u64 v[172:173], v[170:171], 1, s[72:73]
	v_lshl_add_u64 v[128:129], v[160:161], 1, v[172:173]
	global_load_dwordx4 v[186:189], v[128:129], off
	global_load_dwordx4 v[190:193], v[128:129], off offset:256
	v_mov_b32_e32 v129, v161
	v_add_u32_e32 v128, 0x8000, v160
	v_add_u32_e32 v130, 0x10000, v160
	v_mov_b32_e32 v133, v161
	v_add_u32_e32 v132, 0x18000, v160
	v_lshl_add_u64 v[128:129], v[128:129], 1, v[172:173]
	v_lshl_add_u64 v[130:131], v[130:131], 1, v[172:173]
	v_lshl_add_u64 v[182:183], v[132:133], 1, v[172:173]
	global_load_dwordx4 v[148:151], v[128:129], off
	global_load_dwordx4 v[144:147], v[128:129], off offset:256
	global_load_dwordx4 v[140:143], v[130:131], off
	global_load_dwordx4 v[136:139], v[130:131], off offset:256
	global_load_dwordx4 v[132:135], v[182:183], off
	s_nop 0
	global_load_dwordx4 v[128:131], v[182:183], off offset:256
	v_and_b32_e32 v182, 64, v180
	v_mov_b32_e32 v183, v161
	v_add_u32_e32 v204, 64, v182
	v_add_u32_e32 v182, v160, v170
	v_cmp_eq_u32_e32 vcc, 0, v194
	v_lshl_add_u64 v[194:195], v[182:183], 1, s[72:73]
	s_lshl_b32 s0, s0, 2
	v_xor_b32_e32 v171, 16, v180
	s_or_b32 s13, s0, s34
	v_cmp_lt_i32_e64 s[0:1], v171, v204
	s_waitcnt vmcnt(0)
	v_lshlrev_b32_e32 v196, 16, v186
	v_and_b32_e32 v197, 0xffff0000, v186
	v_lshlrev_b32_e32 v186, 16, v187
	v_and_b32_e32 v187, 0xffff0000, v187
	v_lshlrev_b32_e32 v198, 16, v188
	v_and_b32_e32 v199, 0xffff0000, v188
	v_lshlrev_b32_e32 v188, 16, v189
	v_and_b32_e32 v189, 0xffff0000, v189
	v_lshlrev_b32_e32 v200, 16, v190
	v_and_b32_e32 v201, 0xffff0000, v190
	v_lshlrev_b32_e32 v190, 16, v191
	v_and_b32_e32 v191, 0xffff0000, v191
	v_lshlrev_b32_e32 v202, 16, v192
	v_and_b32_e32 v203, 0xffff0000, v192
	v_lshlrev_b32_e32 v192, 16, v193
	v_and_b32_e32 v193, 0xffff0000, v193
	v_pk_add_f32 v[126:127], v[126:127], v[186:187]
	v_pk_add_f32 v[124:125], v[124:125], v[196:197]
	v_pk_add_f32 v[122:123], v[122:123], v[188:189]
	v_pk_add_f32 v[120:121], v[120:121], v[198:199]
	v_pk_add_f32 v[118:119], v[118:119], v[190:191]
	v_pk_add_f32 v[116:117], v[116:117], v[200:201]
	v_pk_add_f32 v[186:187], v[114:115], v[192:193]
	v_pk_add_f32 v[188:189], v[112:113], v[202:203]
	v_cvt_pk_bf16_f32 v112, v124, v125
	v_cvt_pk_bf16_f32 v113, v126, v127
	v_cvt_pk_bf16_f32 v114, v120, v121
	v_cvt_pk_bf16_f32 v115, v122, v123
	v_mul_f32_e32 v125, v125, v125
	v_mul_f32_e32 v127, v127, v127
	v_mul_f32_e32 v121, v121, v121
	v_mul_f32_e32 v123, v123, v123
	v_mul_f32_e32 v183, v117, v117
	v_mul_f32_e32 v190, v119, v119
	v_mul_f32_e32 v191, v189, v189
	v_mul_f32_e32 v192, v187, v187
	v_fmac_f32_e32 v125, v124, v124
	v_fmac_f32_e32 v127, v126, v126
	v_fmac_f32_e32 v121, v120, v120
	v_fmac_f32_e32 v123, v122, v122
	v_fmac_f32_e32 v183, v116, v116
	v_fmac_f32_e32 v190, v118, v118
	v_fmac_f32_e32 v191, v188, v188
	v_fmac_f32_e32 v192, v186, v186
	global_store_dwordx4 v[194:195], v[112:115], off
	v_cndmask_b32_e64 v171, v180, v171, s[0:1]
	v_add_u32_e32 v120, 0x80, v182
	v_add_f32_e32 v112, v125, v127
	v_add_f32_e32 v113, v121, v123
	v_add_f32_e32 v114, v183, v190
	v_add_f32_e32 v115, v191, v192
	v_add_f32_e32 v112, v112, v113
	v_add_f32_e32 v113, v114, v115
	v_add_f32_e32 v113, v112, v113
	v_lshlrev_b32_e32 v112, 2, v171
	v_mov_b32_e32 v121, v161
	v_lshl_add_u64 v[120:121], v[120:121], 1, s[72:73]
	v_cvt_pk_bf16_f32 v116, v116, v117
	v_cvt_pk_bf16_f32 v117, v118, v119
	s_waitcnt lgkmcnt(0)
	v_mov_b32_e32 v114, v113
	v_mov_b32_e32 v253, v113
	s_nop 1
	v_permlane16_swap_b32_e32 v114, v253
	v_add_f32_e32 v114, v114, v253
	v_xor_b32_e32 v113, 32, v180
	v_cmp_lt_i32_e64 s[0:1], v113, v204
	v_cvt_pk_bf16_f32 v118, v188, v189
	v_cvt_pk_bf16_f32 v119, v186, v187
	global_store_dwordx4 v[120:121], v[116:119], off
	s_nop 0
	v_cndmask_b32_e64 v113, v180, v113, s[0:1]
	v_lshlrev_b32_e32 v113, 2, v113
	v_mov_b32_e32 v115, v114
	v_mov_b32_e32 v253, v114
	s_nop 1
	v_permlane32_swap_b32_e32 v115, v253
	v_add_f32_e32 v116, v115, v253
	s_and_saveexec_b64 s[0:1], vcc
	s_cbranch_execz .LBB0_1285
	s_waitcnt lgkmcnt(0)
	v_lshl_add_u32 v114, v181, 5, s13
	v_mov_b32_e32 v115, v161
	v_lshl_add_u64 v[114:115], v[114:115], 2, s[76:77]
	global_store_dword v[114:115], v116, off
.LBB0_1285:
	s_or_b64 exec, exec, s[0:1]
	v_add_u32_e32 v114, 16, v181
	v_lshl_add_u32 v116, v114, 11, v170
	v_lshlrev_b32_e32 v118, 16, v148
	v_and_b32_e32 v119, 0xffff0000, v148
	v_lshlrev_b32_e32 v120, 16, v149
	v_and_b32_e32 v121, 0xffff0000, v149
	v_lshlrev_b32_e32 v122, 16, v150
	v_and_b32_e32 v123, 0xffff0000, v150
	v_mov_b32_e32 v117, v161
	v_lshlrev_b32_e32 v124, 16, v151
	v_and_b32_e32 v125, 0xffff0000, v151
	v_pk_add_f32 v[110:111], v[110:111], v[120:121]
	v_pk_add_f32 v[108:109], v[108:109], v[118:119]
	v_pk_add_f32 v[120:121], v[104:105], v[122:123]
	v_cvt_pk_bf16_f32 v104, v108, v109
	v_cvt_pk_bf16_f32 v105, v110, v111
	v_lshl_add_u64 v[122:123], v[116:117], 1, s[72:73]
	v_pk_add_f32 v[118:119], v[106:107], v[124:125]
	v_cvt_pk_bf16_f32 v106, v120, v121
	s_nop 0
	v_cvt_pk_bf16_f32 v107, v118, v119
	global_store_dwordx4 v[122:123], v[104:107], off
	s_nop 1
	v_mul_f32_e32 v104, v109, v109
	v_mul_f32_e32 v105, v111, v111
	v_fmac_f32_e32 v104, v108, v108
	v_fmac_f32_e32 v105, v110, v110
	v_add_f32_e32 v104, v104, v105
	v_mul_f32_e32 v105, v121, v121
	v_mul_f32_e32 v106, v119, v119
	v_fmac_f32_e32 v105, v120, v120
	v_fmac_f32_e32 v106, v118, v118
	v_add_f32_e32 v105, v105, v106
	s_waitcnt lgkmcnt(0)
	v_add_f32_e32 v115, v104, v105
	v_lshlrev_b32_e32 v104, 16, v144
	v_and_b32_e32 v105, 0xffff0000, v144
	v_lshlrev_b32_e32 v106, 16, v145
	v_and_b32_e32 v107, 0xffff0000, v145
	v_lshlrev_b32_e32 v110, 16, v147
	v_and_b32_e32 v111, 0xffff0000, v147
	v_pk_add_f32 v[102:103], v[102:103], v[106:107]
	v_pk_add_f32 v[100:101], v[100:101], v[104:105]
	v_lshlrev_b32_e32 v108, 16, v146
	v_and_b32_e32 v109, 0xffff0000, v146
	v_pk_add_f32 v[104:105], v[98:99], v[110:111]
	v_mul_f32_e32 v98, v101, v101
	v_mul_f32_e32 v99, v103, v103
	v_pk_add_f32 v[96:97], v[96:97], v[108:109]
	v_fmac_f32_e32 v98, v100, v100
	v_fmac_f32_e32 v99, v102, v102
	v_add_f32_e32 v98, v98, v99
	v_mul_f32_e32 v99, v97, v97
	v_mul_f32_e32 v106, v105, v105
	v_fmac_f32_e32 v99, v96, v96
	v_fmac_f32_e32 v106, v104, v104
	v_add_f32_e32 v99, v99, v106
	v_add_f32_e32 v98, v98, v99
	v_add_f32_e32 v107, v115, v98
	v_cvt_pk_bf16_f32 v98, v100, v101
	v_cvt_pk_bf16_f32 v99, v102, v103
	v_cvt_pk_bf16_f32 v100, v96, v97
	v_add_u32_e32 v106, 0x80, v116
	s_waitcnt lgkmcnt(0)
	v_mov_b32_e32 v108, v107
	v_mov_b32_e32 v253, v107
	s_nop 1
	v_permlane16_swap_b32_e32 v108, v253
	v_add_f32_e32 v96, v108, v253
	v_mov_b32_e32 v107, v161
	v_lshl_add_u64 v[102:103], v[106:107], 1, s[72:73]
	v_cvt_pk_bf16_f32 v101, v104, v105
	global_store_dwordx4 v[102:103], v[98:101], off
	v_mov_b32_e32 v97, v96
	v_mov_b32_e32 v253, v96
	s_nop 1
	v_permlane32_swap_b32_e32 v97, v253
	v_add_f32_e32 v98, v97, v253
	s_and_saveexec_b64 s[0:1], vcc
	s_cbranch_execz .LBB0_1287
	s_waitcnt lgkmcnt(0)
	v_lshl_add_u32 v96, v114, 5, s13
	v_mov_b32_e32 v97, v161
	v_lshl_add_u64 v[96:97], v[96:97], 2, s[76:77]
	global_store_dword v[96:97], v98, off
.LBB0_1287:
	s_or_b64 exec, exec, s[0:1]
	v_add_u32_e32 v96, 32, v181
	v_lshl_add_u32 v98, v96, 11, v170
	v_lshlrev_b32_e32 v100, 16, v140
	v_and_b32_e32 v101, 0xffff0000, v140
	v_lshlrev_b32_e32 v102, 16, v141
	v_and_b32_e32 v103, 0xffff0000, v141
	v_lshlrev_b32_e32 v104, 16, v142
	v_and_b32_e32 v105, 0xffff0000, v142
	v_mov_b32_e32 v99, v161
	v_lshlrev_b32_e32 v106, 16, v143
	v_and_b32_e32 v107, 0xffff0000, v143
	v_pk_add_f32 v[94:95], v[94:95], v[102:103]
	v_pk_add_f32 v[92:93], v[92:93], v[100:101]
	v_pk_add_f32 v[102:103], v[88:89], v[104:105]
	v_cvt_pk_bf16_f32 v88, v92, v93
	v_cvt_pk_bf16_f32 v89, v94, v95
	v_lshl_add_u64 v[104:105], v[98:99], 1, s[72:73]
	v_pk_add_f32 v[100:101], v[90:91], v[106:107]
	v_cvt_pk_bf16_f32 v90, v102, v103
	s_nop 0
	v_cvt_pk_bf16_f32 v91, v100, v101
	global_store_dwordx4 v[104:105], v[88:91], off
	s_nop 1
	v_mul_f32_e32 v88, v93, v93
	v_mul_f32_e32 v89, v95, v95
	v_fmac_f32_e32 v88, v92, v92
	v_fmac_f32_e32 v89, v94, v94
	v_add_f32_e32 v88, v88, v89
	v_mul_f32_e32 v89, v103, v103
	v_mul_f32_e32 v90, v101, v101
	v_fmac_f32_e32 v89, v102, v102
	v_fmac_f32_e32 v90, v100, v100
	v_add_f32_e32 v89, v89, v90
	s_waitcnt lgkmcnt(0)
	v_add_f32_e32 v97, v88, v89
	v_lshlrev_b32_e32 v88, 16, v136
	v_and_b32_e32 v89, 0xffff0000, v136
	v_lshlrev_b32_e32 v90, 16, v137
	v_and_b32_e32 v91, 0xffff0000, v137
	v_lshlrev_b32_e32 v94, 16, v139
	v_and_b32_e32 v95, 0xffff0000, v139
	v_pk_add_f32 v[86:87], v[86:87], v[90:91]
	v_pk_add_f32 v[84:85], v[84:85], v[88:89]
	v_lshlrev_b32_e32 v92, 16, v138
	v_and_b32_e32 v93, 0xffff0000, v138
	v_pk_add_f32 v[88:89], v[82:83], v[94:95]
	v_mul_f32_e32 v82, v85, v85
	v_mul_f32_e32 v83, v87, v87
	v_pk_add_f32 v[80:81], v[80:81], v[92:93]
	v_fmac_f32_e32 v82, v84, v84
	v_fmac_f32_e32 v83, v86, v86
	v_add_f32_e32 v82, v82, v83
	v_mul_f32_e32 v83, v81, v81
	v_mul_f32_e32 v90, v89, v89
	v_fmac_f32_e32 v83, v80, v80
	v_fmac_f32_e32 v90, v88, v88
	v_add_f32_e32 v83, v83, v90
	v_add_f32_e32 v82, v82, v83
	v_add_f32_e32 v91, v97, v82
	v_cvt_pk_bf16_f32 v82, v84, v85
	v_cvt_pk_bf16_f32 v83, v86, v87
	v_cvt_pk_bf16_f32 v84, v80, v81
	v_add_u32_e32 v90, 0x80, v98
	s_waitcnt lgkmcnt(0)
	v_mov_b32_e32 v92, v91
	v_mov_b32_e32 v253, v91
	s_nop 1
	v_permlane16_swap_b32_e32 v92, v253
	v_add_f32_e32 v80, v92, v253
	v_mov_b32_e32 v91, v161
	v_lshl_add_u64 v[86:87], v[90:91], 1, s[72:73]
	v_cvt_pk_bf16_f32 v85, v88, v89
	global_store_dwordx4 v[86:87], v[82:85], off
	v_mov_b32_e32 v81, v80
	v_mov_b32_e32 v253, v80
	s_nop 1
	v_permlane32_swap_b32_e32 v81, v253
	v_add_f32_e32 v82, v81, v253
	s_and_saveexec_b64 s[0:1], vcc
	s_cbranch_execz .LBB0_1289
	s_waitcnt lgkmcnt(0)
	v_lshl_add_u32 v80, v96, 5, s13
	v_mov_b32_e32 v81, v161
	v_lshl_add_u64 v[80:81], v[80:81], 2, s[76:77]
	global_store_dword v[80:81], v82, off
.LBB0_1289:
	s_or_b64 exec, exec, s[0:1]
	v_add_u32_e32 v80, 48, v181
	v_lshl_add_u32 v82, v80, 11, v170
	v_lshlrev_b32_e32 v84, 16, v132
	v_and_b32_e32 v85, 0xffff0000, v132
	v_lshlrev_b32_e32 v86, 16, v133
	v_and_b32_e32 v87, 0xffff0000, v133
	v_lshlrev_b32_e32 v88, 16, v134
	v_and_b32_e32 v89, 0xffff0000, v134
	v_mov_b32_e32 v83, v161
	v_lshlrev_b32_e32 v90, 16, v135
	v_and_b32_e32 v91, 0xffff0000, v135
	v_pk_add_f32 v[78:79], v[78:79], v[86:87]
	v_pk_add_f32 v[76:77], v[76:77], v[84:85]
	v_pk_add_f32 v[86:87], v[72:73], v[88:89]
	v_cvt_pk_bf16_f32 v72, v76, v77
	v_cvt_pk_bf16_f32 v73, v78, v79
	v_lshl_add_u64 v[88:89], v[82:83], 1, s[72:73]
	v_pk_add_f32 v[84:85], v[74:75], v[90:91]
	v_cvt_pk_bf16_f32 v74, v86, v87
	s_nop 0
	v_cvt_pk_bf16_f32 v75, v84, v85
	global_store_dwordx4 v[88:89], v[72:75], off
	s_nop 1
	v_mul_f32_e32 v72, v77, v77
	v_mul_f32_e32 v73, v79, v79
	v_fmac_f32_e32 v72, v76, v76
	v_fmac_f32_e32 v73, v78, v78
	v_add_f32_e32 v72, v72, v73
	v_mul_f32_e32 v73, v87, v87
	v_mul_f32_e32 v74, v85, v85
	v_fmac_f32_e32 v73, v86, v86
	v_fmac_f32_e32 v74, v84, v84
	v_add_f32_e32 v73, v73, v74
	s_waitcnt lgkmcnt(0)
	v_add_f32_e32 v81, v72, v73
	v_lshlrev_b32_e32 v72, 16, v128
	v_and_b32_e32 v73, 0xffff0000, v128
	v_lshlrev_b32_e32 v74, 16, v129
	v_and_b32_e32 v75, 0xffff0000, v129
	v_lshlrev_b32_e32 v78, 16, v131
	v_and_b32_e32 v79, 0xffff0000, v131
	v_pk_add_f32 v[70:71], v[70:71], v[74:75]
	v_pk_add_f32 v[68:69], v[68:69], v[72:73]
	v_lshlrev_b32_e32 v76, 16, v130
	v_and_b32_e32 v77, 0xffff0000, v130
	v_pk_add_f32 v[72:73], v[66:67], v[78:79]
	v_mul_f32_e32 v66, v69, v69
	v_mul_f32_e32 v67, v71, v71
	v_pk_add_f32 v[64:65], v[64:65], v[76:77]
	v_fmac_f32_e32 v66, v68, v68
	v_fmac_f32_e32 v67, v70, v70
	v_add_f32_e32 v66, v66, v67
	v_mul_f32_e32 v67, v65, v65
	v_mul_f32_e32 v74, v73, v73
	v_fmac_f32_e32 v67, v64, v64
	v_fmac_f32_e32 v74, v72, v72
	v_add_f32_e32 v67, v67, v74
	v_add_f32_e32 v66, v66, v67
	v_add_f32_e32 v75, v81, v66
	v_cvt_pk_bf16_f32 v66, v68, v69
	v_cvt_pk_bf16_f32 v67, v70, v71
	v_cvt_pk_bf16_f32 v68, v64, v65
	v_add_u32_e32 v74, 0x80, v82
	s_waitcnt lgkmcnt(0)
	v_mov_b32_e32 v76, v75
	v_mov_b32_e32 v253, v75
	s_nop 1
	v_permlane16_swap_b32_e32 v76, v253
	v_add_f32_e32 v64, v76, v253
	v_mov_b32_e32 v75, v161
	v_lshl_add_u64 v[70:71], v[74:75], 1, s[72:73]
	v_cvt_pk_bf16_f32 v69, v72, v73
	global_store_dwordx4 v[70:71], v[66:69], off
	v_mov_b32_e32 v65, v64
	v_mov_b32_e32 v253, v64
	s_nop 1
	v_permlane32_swap_b32_e32 v65, v253
	v_add_f32_e32 v66, v65, v253
	s_and_saveexec_b64 s[0:1], vcc
	s_cbranch_execz .LBB0_1291
	s_waitcnt lgkmcnt(0)
	v_lshl_add_u32 v64, v80, 5, s13
	v_mov_b32_e32 v65, v161
	v_lshl_add_u64 v[64:65], v[64:65], 2, s[76:77]
	global_store_dword v[64:65], v66, off
.LBB0_1291:
	s_or_b64 exec, exec, s[0:1]
	v_add_u32_e32 v64, 0x40000, v160
	s_waitcnt lgkmcnt(0)
	v_mov_b32_e32 v65, v161
	v_lshl_add_u64 v[64:65], v[64:65], 1, v[172:173]
	global_load_dwordx4 v[90:93], v[64:65], off
	global_load_dwordx4 v[94:97], v[64:65], off offset:256
	v_add_u32_e32 v64, 0x48000, v160
	v_mov_b32_e32 v65, v161
	v_add_u32_e32 v66, 0x50000, v160
	v_mov_b32_e32 v67, v161
	v_add_u32_e32 v160, 0x58000, v160
	v_lshl_add_u64 v[64:65], v[64:65], 1, v[172:173]
	v_lshl_add_u64 v[66:67], v[66:67], 1, v[172:173]
	v_lshl_add_u64 v[88:89], v[160:161], 1, v[172:173]
	global_load_dwordx4 v[84:87], v[64:65], off
	global_load_dwordx4 v[80:83], v[64:65], off offset:256
	global_load_dwordx4 v[76:79], v[66:67], off
	global_load_dwordx4 v[72:75], v[66:67], off offset:256
	global_load_dwordx4 v[68:71], v[88:89], off
	s_nop 0
	global_load_dwordx4 v[64:67], v[88:89], off offset:256
	v_add_u32_e32 v88, 0x80, v181
	v_lshl_add_u32 v160, v88, 11, v170
	v_lshl_add_u64 v[98:99], v[160:161], 1, s[72:73]
	v_add_u32_e32 v160, 0x80, v160
	s_waitcnt vmcnt(7)
	v_lshlrev_b32_e32 v100, 16, v90
	v_and_b32_e32 v101, 0xffff0000, v90
	v_lshlrev_b32_e32 v90, 16, v91
	v_and_b32_e32 v91, 0xffff0000, v91
	v_lshlrev_b32_e32 v102, 16, v92
	v_and_b32_e32 v103, 0xffff0000, v92
	v_lshlrev_b32_e32 v92, 16, v93
	v_and_b32_e32 v93, 0xffff0000, v93
	s_waitcnt vmcnt(6)
	v_lshlrev_b32_e32 v104, 16, v94
	v_and_b32_e32 v105, 0xffff0000, v94
	v_lshlrev_b32_e32 v94, 16, v95
	v_and_b32_e32 v95, 0xffff0000, v95
	v_lshlrev_b32_e32 v106, 16, v96
	v_and_b32_e32 v107, 0xffff0000, v96
	v_lshlrev_b32_e32 v96, 16, v97
	v_and_b32_e32 v97, 0xffff0000, v97
	v_pk_add_f32 v[62:63], v[62:63], v[90:91]
	v_pk_add_f32 v[60:61], v[60:61], v[100:101]
	v_pk_add_f32 v[58:59], v[58:59], v[92:93]
	v_pk_add_f32 v[56:57], v[56:57], v[102:103]
	v_pk_add_f32 v[54:55], v[54:55], v[94:95]
	v_pk_add_f32 v[52:53], v[52:53], v[104:105]
	v_pk_add_f32 v[90:91], v[50:51], v[96:97]
	v_pk_add_f32 v[92:93], v[48:49], v[106:107]
	v_cvt_pk_bf16_f32 v48, v60, v61
	v_cvt_pk_bf16_f32 v49, v62, v63
	v_cvt_pk_bf16_f32 v50, v56, v57
	v_cvt_pk_bf16_f32 v51, v58, v59
	v_mul_f32_e32 v61, v61, v61
	v_mul_f32_e32 v63, v63, v63
	v_mul_f32_e32 v57, v57, v57
	v_mul_f32_e32 v59, v59, v59
	v_mul_f32_e32 v89, v53, v53
	v_mul_f32_e32 v94, v55, v55
	v_mul_f32_e32 v95, v93, v93
	v_mul_f32_e32 v96, v91, v91
	v_fmac_f32_e32 v61, v60, v60
	v_fmac_f32_e32 v63, v62, v62
	v_fmac_f32_e32 v57, v56, v56
	v_fmac_f32_e32 v59, v58, v58
	v_fmac_f32_e32 v89, v52, v52
	v_fmac_f32_e32 v94, v54, v54
	v_fmac_f32_e32 v95, v92, v92
	v_fmac_f32_e32 v96, v90, v90
	v_add_f32_e32 v56, v61, v63
	v_add_f32_e32 v57, v57, v59
	v_add_f32_e32 v58, v89, v94
	v_add_f32_e32 v59, v95, v96
	v_add_f32_e32 v56, v56, v57
	v_add_f32_e32 v57, v58, v59
	v_add_f32_e32 v56, v56, v57
	global_store_dwordx4 v[98:99], v[48:51], off
	s_nop 1
	v_cvt_pk_bf16_f32 v50, v52, v53
	s_waitcnt lgkmcnt(0)
	v_mov_b32_e32 v57, v56
	v_mov_b32_e32 v253, v56
	s_nop 1
	v_permlane16_swap_b32_e32 v57, v253
	v_add_f32_e32 v48, v57, v253
	v_cvt_pk_bf16_f32 v51, v54, v55
	v_lshl_add_u64 v[54:55], v[160:161], 1, s[72:73]
	v_cvt_pk_bf16_f32 v52, v92, v93
	v_cvt_pk_bf16_f32 v53, v90, v91
	global_store_dwordx4 v[54:55], v[50:53], off
	v_mov_b32_e32 v49, v48
	v_mov_b32_e32 v253, v48
	s_nop 1
	v_permlane32_swap_b32_e32 v49, v253
	v_add_f32_e32 v50, v49, v253
	s_and_saveexec_b64 s[0:1], vcc
	s_cbranch_execz .LBB0_1293
	v_lshl_add_u32 v160, v88, 5, s13
	s_waitcnt lgkmcnt(0)
	v_lshl_add_u64 v[48:49], v[160:161], 2, s[76:77]
	global_store_dword v[48:49], v50, off
.LBB0_1293:
	s_or_b64 exec, exec, s[0:1]
	s_waitcnt vmcnt(7)
	v_lshlrev_b32_e32 v50, 16, v84
	v_and_b32_e32 v51, 0xffff0000, v84
	v_lshlrev_b32_e32 v52, 16, v85
	v_and_b32_e32 v53, 0xffff0000, v85
	v_lshlrev_b32_e32 v54, 16, v86
	v_and_b32_e32 v55, 0xffff0000, v86
	v_pk_add_f32 v[44:45], v[44:45], v[50:51]
	v_pk_add_f32 v[46:47], v[46:47], v[52:53]
	v_pk_add_f32 v[52:53], v[40:41], v[54:55]
	v_cvt_pk_bf16_f32 v40, v44, v45
	v_mul_f32_e32 v45, v45, v45
	v_lshlrev_b32_e32 v56, 16, v87
	v_and_b32_e32 v57, 0xffff0000, v87
	v_fmac_f32_e32 v45, v44, v44
	v_mul_f32_e32 v44, v47, v47
	v_pk_add_f32 v[50:51], v[42:43], v[56:57]
	v_fmac_f32_e32 v44, v46, v46
	v_cvt_pk_bf16_f32 v41, v46, v47
	v_add_f32_e32 v44, v45, v44
	v_mul_f32_e32 v45, v53, v53
	v_mul_f32_e32 v46, v51, v51
	v_fmac_f32_e32 v45, v52, v52
	v_fmac_f32_e32 v46, v50, v50
	v_add_f32_e32 v45, v45, v46
	s_waitcnt lgkmcnt(0)
	v_add_f32_e32 v49, v44, v45
	s_waitcnt vmcnt(6)
	v_lshlrev_b32_e32 v44, 16, v80
	v_and_b32_e32 v45, 0xffff0000, v80
	v_lshlrev_b32_e32 v46, 16, v81
	v_and_b32_e32 v47, 0xffff0000, v81
	v_cvt_pk_bf16_f32 v42, v52, v53
	v_cvt_pk_bf16_f32 v43, v50, v51
	v_lshlrev_b32_e32 v50, 16, v82
	v_and_b32_e32 v51, 0xffff0000, v82
	v_pk_add_f32 v[38:39], v[38:39], v[46:47]
	v_pk_add_f32 v[36:37], v[36:37], v[44:45]
	v_lshlrev_b32_e32 v52, 16, v83
	v_and_b32_e32 v53, 0xffff0000, v83
	v_pk_add_f32 v[46:47], v[32:33], v[50:51]
	v_mul_f32_e32 v32, v37, v37
	v_mul_f32_e32 v33, v39, v39
	v_pk_add_f32 v[44:45], v[34:35], v[52:53]
	v_fmac_f32_e32 v32, v36, v36
	v_fmac_f32_e32 v33, v38, v38
	v_add_f32_e32 v32, v32, v33
	v_mul_f32_e32 v33, v47, v47
	v_mul_f32_e32 v34, v45, v45
	v_fmac_f32_e32 v33, v46, v46
	v_fmac_f32_e32 v34, v44, v44
	v_add_f32_e32 v33, v33, v34
	v_add_f32_e32 v32, v32, v33
	v_add_f32_e32 v32, v49, v32
	v_add_u32_e32 v48, 0x90, v181
	v_lshl_add_u32 v160, v48, 11, v170
	v_lshl_add_u64 v[54:55], v[160:161], 1, s[72:73]
	v_add_u32_e32 v160, 0x80, v160
	s_waitcnt lgkmcnt(0)
	v_mov_b32_e32 v33, v32
	v_mov_b32_e32 v253, v32
	s_nop 1
	v_permlane16_swap_b32_e32 v33, v253
	v_add_f32_e32 v32, v33, v253
	global_store_dwordx4 v[54:55], v[40:43], off
	v_cvt_pk_bf16_f32 v34, v36, v37
	v_cvt_pk_bf16_f32 v35, v38, v39
	v_lshl_add_u64 v[38:39], v[160:161], 1, s[72:73]
	v_cvt_pk_bf16_f32 v36, v46, v47
	v_cvt_pk_bf16_f32 v37, v44, v45
	global_store_dwordx4 v[38:39], v[34:37], off
	v_mov_b32_e32 v33, v32
	v_mov_b32_e32 v253, v32
	s_nop 1
	v_permlane32_swap_b32_e32 v33, v253
	v_add_f32_e32 v34, v33, v253
	s_and_saveexec_b64 s[0:1], vcc
	s_cbranch_execz .LBB0_1295
	v_lshl_add_u32 v160, v48, 5, s13
	s_waitcnt lgkmcnt(0)
	v_lshl_add_u64 v[32:33], v[160:161], 2, s[76:77]
	global_store_dword v[32:33], v34, off
.LBB0_1295:
	s_or_b64 exec, exec, s[0:1]
	s_waitcnt vmcnt(7)
	v_lshlrev_b32_e32 v34, 16, v76
	v_and_b32_e32 v35, 0xffff0000, v76
	v_lshlrev_b32_e32 v36, 16, v77
	v_and_b32_e32 v37, 0xffff0000, v77
	v_lshlrev_b32_e32 v38, 16, v78
	v_and_b32_e32 v39, 0xffff0000, v78
	v_pk_add_f32 v[28:29], v[28:29], v[34:35]
	v_pk_add_f32 v[30:31], v[30:31], v[36:37]
	v_pk_add_f32 v[36:37], v[24:25], v[38:39]
	v_cvt_pk_bf16_f32 v24, v28, v29
	v_mul_f32_e32 v29, v29, v29
	v_lshlrev_b32_e32 v40, 16, v79
	v_and_b32_e32 v41, 0xffff0000, v79
	v_fmac_f32_e32 v29, v28, v28
	v_mul_f32_e32 v28, v31, v31
	v_pk_add_f32 v[34:35], v[26:27], v[40:41]
	v_fmac_f32_e32 v28, v30, v30
	v_cvt_pk_bf16_f32 v25, v30, v31
	v_add_f32_e32 v28, v29, v28
	v_mul_f32_e32 v29, v37, v37
	v_mul_f32_e32 v30, v35, v35
	v_fmac_f32_e32 v29, v36, v36
	v_fmac_f32_e32 v30, v34, v34
	v_add_f32_e32 v29, v29, v30
	s_waitcnt lgkmcnt(0)
	v_add_f32_e32 v33, v28, v29
	s_waitcnt vmcnt(6)
	v_lshlrev_b32_e32 v28, 16, v72
	v_and_b32_e32 v29, 0xffff0000, v72
	v_lshlrev_b32_e32 v30, 16, v73
	v_and_b32_e32 v31, 0xffff0000, v73
	v_cvt_pk_bf16_f32 v26, v36, v37
	v_cvt_pk_bf16_f32 v27, v34, v35
	v_lshlrev_b32_e32 v34, 16, v74
	v_and_b32_e32 v35, 0xffff0000, v74
	v_pk_add_f32 v[22:23], v[22:23], v[30:31]
	v_pk_add_f32 v[20:21], v[20:21], v[28:29]
	v_lshlrev_b32_e32 v36, 16, v75
	v_and_b32_e32 v37, 0xffff0000, v75
	v_pk_add_f32 v[30:31], v[16:17], v[34:35]
	v_mul_f32_e32 v16, v21, v21
	v_mul_f32_e32 v17, v23, v23
	v_pk_add_f32 v[28:29], v[18:19], v[36:37]
	v_fmac_f32_e32 v16, v20, v20
	v_fmac_f32_e32 v17, v22, v22
	v_add_f32_e32 v16, v16, v17
	v_mul_f32_e32 v17, v31, v31
	v_mul_f32_e32 v18, v29, v29
	v_fmac_f32_e32 v17, v30, v30
	v_fmac_f32_e32 v18, v28, v28
	v_add_f32_e32 v17, v17, v18
	v_add_f32_e32 v16, v16, v17
	v_add_f32_e32 v16, v33, v16
	v_add_u32_e32 v32, 0xa0, v181
	v_lshl_add_u32 v160, v32, 11, v170
	v_lshl_add_u64 v[38:39], v[160:161], 1, s[72:73]
	v_add_u32_e32 v160, 0x80, v160
	s_waitcnt lgkmcnt(0)
	v_mov_b32_e32 v17, v16
	v_mov_b32_e32 v253, v16
	s_nop 1
	v_permlane16_swap_b32_e32 v17, v253
	v_add_f32_e32 v16, v17, v253
	global_store_dwordx4 v[38:39], v[24:27], off
	v_cvt_pk_bf16_f32 v18, v20, v21
	v_cvt_pk_bf16_f32 v19, v22, v23
	v_lshl_add_u64 v[22:23], v[160:161], 1, s[72:73]
	v_cvt_pk_bf16_f32 v20, v30, v31
	v_cvt_pk_bf16_f32 v21, v28, v29
	global_store_dwordx4 v[22:23], v[18:21], off
	v_mov_b32_e32 v17, v16
	v_mov_b32_e32 v253, v16
	s_nop 1
	v_permlane32_swap_b32_e32 v17, v253
	v_add_f32_e32 v18, v17, v253
	s_and_saveexec_b64 s[0:1], vcc
	s_cbranch_execz .LBB0_1297
	v_lshl_add_u32 v160, v32, 5, s13
	s_waitcnt lgkmcnt(0)
	v_lshl_add_u64 v[16:17], v[160:161], 2, s[76:77]
	global_store_dword v[16:17], v18, off
.LBB0_1297:
	s_or_b64 exec, exec, s[0:1]
	s_waitcnt vmcnt(7)
	v_lshlrev_b32_e32 v18, 16, v68
	v_and_b32_e32 v19, 0xffff0000, v68
	v_lshlrev_b32_e32 v20, 16, v69
	v_and_b32_e32 v21, 0xffff0000, v69
	v_lshlrev_b32_e32 v22, 16, v70
	v_and_b32_e32 v23, 0xffff0000, v70
	v_pk_add_f32 v[12:13], v[12:13], v[18:19]
	v_pk_add_f32 v[14:15], v[14:15], v[20:21]
	v_pk_add_f32 v[20:21], v[8:9], v[22:23]
	v_cvt_pk_bf16_f32 v8, v12, v13
	v_mul_f32_e32 v13, v13, v13
	v_lshlrev_b32_e32 v24, 16, v71
	v_and_b32_e32 v25, 0xffff0000, v71
	v_fmac_f32_e32 v13, v12, v12
	v_mul_f32_e32 v12, v15, v15
	v_pk_add_f32 v[18:19], v[10:11], v[24:25]
	v_fmac_f32_e32 v12, v14, v14
	v_cvt_pk_bf16_f32 v9, v14, v15
	v_add_f32_e32 v12, v13, v12
	v_mul_f32_e32 v13, v21, v21
	v_mul_f32_e32 v14, v19, v19
	v_fmac_f32_e32 v13, v20, v20
	v_fmac_f32_e32 v14, v18, v18
	v_add_f32_e32 v13, v13, v14
	s_waitcnt lgkmcnt(0)
	v_add_f32_e32 v17, v12, v13
	s_waitcnt vmcnt(6)
	v_lshlrev_b32_e32 v12, 16, v64
	v_and_b32_e32 v13, 0xffff0000, v64
	v_lshlrev_b32_e32 v14, 16, v65
	v_and_b32_e32 v15, 0xffff0000, v65
	v_cvt_pk_bf16_f32 v10, v20, v21
	v_cvt_pk_bf16_f32 v11, v18, v19
	v_lshlrev_b32_e32 v18, 16, v66
	v_and_b32_e32 v19, 0xffff0000, v66
	v_pk_add_f32 v[6:7], v[6:7], v[14:15]
	v_pk_add_f32 v[4:5], v[4:5], v[12:13]
	v_lshlrev_b32_e32 v20, 16, v67
	v_and_b32_e32 v21, 0xffff0000, v67
	v_pk_add_f32 v[14:15], v[0:1], v[18:19]
	v_mul_f32_e32 v0, v5, v5
	v_mul_f32_e32 v1, v7, v7
	v_pk_add_f32 v[12:13], v[2:3], v[20:21]
	v_fmac_f32_e32 v0, v4, v4
	v_fmac_f32_e32 v1, v6, v6
	v_add_f32_e32 v0, v0, v1
	v_mul_f32_e32 v1, v15, v15
	v_mul_f32_e32 v2, v13, v13
	v_fmac_f32_e32 v1, v14, v14
	v_fmac_f32_e32 v2, v12, v12
	v_add_f32_e32 v1, v1, v2
	v_add_f32_e32 v0, v0, v1
	v_add_f32_e32 v0, v17, v0
	v_add_u32_e32 v16, 0xb0, v181
	v_lshl_add_u32 v160, v16, 11, v170
	v_lshl_add_u64 v[22:23], v[160:161], 1, s[72:73]
	v_add_u32_e32 v160, 0x80, v160
	s_waitcnt lgkmcnt(0)
	v_mov_b32_e32 v1, v0
	v_mov_b32_e32 v253, v0
	s_nop 1
	v_permlane16_swap_b32_e32 v1, v253
	v_add_f32_e32 v0, v1, v253
	global_store_dwordx4 v[22:23], v[8:11], off
	v_cvt_pk_bf16_f32 v2, v4, v5
	v_cvt_pk_bf16_f32 v3, v6, v7
	v_lshl_add_u64 v[6:7], v[160:161], 1, s[72:73]
	v_cvt_pk_bf16_f32 v4, v14, v15
	v_cvt_pk_bf16_f32 v5, v12, v13
	global_store_dwordx4 v[6:7], v[2:5], off
	v_mov_b32_e32 v1, v0
	v_mov_b32_e32 v253, v0
	s_nop 1
	v_permlane32_swap_b32_e32 v1, v253
	v_add_f32_e32 v2, v1, v253
	s_and_saveexec_b64 s[0:1], vcc
	s_cbranch_execz .LBB0_1299
	v_lshl_add_u32 v160, v16, 5, s13
	s_waitcnt lgkmcnt(0)
	v_lshl_add_u64 v[0:1], v[160:161], 2, s[76:77]
	global_store_dword v[0:1], v2, off
